# P6 up-projection epilogues: per-row-group sum-of-squares loads hoisted, per-group vmcnt(0) drains removed; plus P8 epilogue fix, sc1 epilogue stores, nt streamed-once loads, MLA role-split
# speedup vs baseline: 1.0133x; 1.0023x over previous
; __device__ __forceinline__ void st4(bf16_t* p, f32x4 v) { u32x2 w; w.x = cvt_pk_bf16(v[0], v[1]); w.y = cvt_pk_bf16(v[2], v[3]); *(u32x2*)p = w; }
;     __device__ __forceinline__ void operator()(const f32x4 (&acc)[2][2][4][2], const Unit& u, int wr, int wc, int fr, int fq) const {
;     ...
;             for (int m = 0; m < 4; ++m) { const int row = row0 + ai * HALF + m * 16; const f32x4 sq = *(const f32x4*)(SSQQ + row * 4);
;                 const float sc = C2M / sqrtf(((sq[0] + sq[1]) + (sq[2] + sq[3])) * (1.f / 256.f) + NEPS);
;                 bf16_t* qrow = QM + (size_t)row * 768;
;                 if (u.pn < 2) {
; #pragma unroll
;                     for (int bj = 0; bj < 2; ++bj)
; #pragma unroll
;                         for (int n = 0; n < 2; ++n) { const int c = u.pn * BM + bj * HALF + wc * 32 + n * 16 + 4 * fq; st4(qrow + (c >> 6) * 96 + (c & 63), acc[ai][bj][m][n] * sc); }
;                 } else {
;                     const int srow = row & (SEQL - 1), prow = srow >> 6, pcol = srow & 63; const int a = fq >> 1, e0 = 4 * (fq & 1), pos = a ? pcol : prow;
; #pragma unroll
;                     for (int bj = 0; bj < 2; ++bj) { f32x4 y1, y2; rope4(acc[ai][bj][m][0] * sc, acc[ai][bj][m][1] * sc, ropeM + (pos * 8 + e0) * 2, y1, y2);
;                         bf16_t* hp = qrow + (4 * bj + wc) * 96 + 64; st4(hp + 16 * a + e0, y1); st4(hp + 16 * a + 8 + e0, y2); }
.LBB0_618:
	s_lshl_b32 s0, s0, 8
	v_mov_b32_e32 v162, v145
	v_mov_b32_e32 v138, v148
	s_add_i32 s0, s0, s55
	s_cmp_gt_i32 s10, 1
	v_add_u32_e32 v156, s0, v162
	v_lshlrev_b32_e32 v140, 2, v156
	v_ashrrev_i32_e32 v141, 31, v140
	v_lshl_add_u64 v[140:141], v[140:141], 2, s[16:17]
	global_load_dwordx4 v[190:193], v[140:141], off offset:256
	global_load_dwordx4 v[194:197], v[140:141], off offset:512
	global_load_dwordx4 v[198:201], v[140:141], off offset:768
	global_load_dwordx4 v[202:205], v[140:141], off offset:2048
	global_load_dwordx4 v[206:209], v[140:141], off offset:2304
	global_load_dwordx4 v[210:213], v[140:141], off offset:2560
	global_load_dwordx4 v[214:217], v[140:141], off offset:2816
	global_load_dwordx4 v[140:143], v[140:141], off
	v_lshlrev_b32_e32 v132, 2, v138
	v_cmp_gt_u32_e64 s[6:7], 2, v138
	v_lshlrev_b32_e32 v138, 3, v138
	s_cselect_b64 s[84:85], -1, 0
	v_and_b32_e32 v155, 4, v132
	v_and_b32_e32 v138, -16, v138
	v_ashrrev_i32_e32 v139, 31, v138
	s_waitcnt vmcnt(0)
	v_add_f32_e32 v140, v140, v141
	v_add_f32_e32 v141, v142, v143
	v_add_f32_e32 v140, v140, v141
	v_fmamk_f32 v140, v140, 0x3b800000, v153
	v_cmp_gt_f32_e32 vcc, s33, v140
	v_mul_f32_e32 v141, 0x4f800000, v140
	s_nop 0
	v_cndmask_b32_e32 v140, v140, v141, vcc
	v_sqrt_f32_e32 v141, v140
	s_nop 0
	v_add_u32_e32 v142, -1, v141
	v_fma_f32 v143, -v142, v141, v140
	v_cmp_ge_f32_e64 s[0:1], 0, v143
	v_add_u32_e32 v143, 1, v141
	s_nop 0
	v_cndmask_b32_e64 v142, v141, v142, s[0:1]
	v_fma_f32 v141, -v143, v141, v140
	v_cmp_lt_f32_e64 s[0:1], 0, v141
	s_nop 1
	v_cndmask_b32_e64 v141, v142, v143, s[0:1]
	v_mul_f32_e32 v142, 0x37800000, v141
	v_cndmask_b32_e32 v141, v141, v142, vcc
	v_cmp_class_f32_e32 vcc, v140, v154
	s_nop 1
	v_cndmask_b32_e32 v140, v141, v140, vcc
	v_div_scale_f32 v141, s[0:1], v140, v140, s58
	v_rcp_f32_e32 v142, v141
	s_nop 0
	v_fma_f32 v143, -v141, v142, 1.0
	v_fmac_f32_e32 v142, v143, v142
	v_div_scale_f32 v143, vcc, s58, v140, s58
	v_mul_f32_e32 v144, v143, v142
	v_fma_f32 v146, -v141, v144, v143
	v_fmac_f32_e32 v144, v146, v142
	v_fma_f32 v141, -v141, v144, v143
	v_div_fmas_f32 v141, v141, v142, v144
	v_div_fixup_f32 v144, v141, v140, s58
	v_mov_b64_e32 v[140:141], s[22:23]
	v_mad_i64_i32 v[146:147], s[0:1], v156, s59, v[140:141]
	s_mov_b64 s[0:1], -1
	s_and_b64 vcc, exec, s[84:85]
	v_lshlrev_b32_e32 v140, 1, v155
	s_cbranch_vccz .LBB0_620
	v_lshrrev_b32_e32 v141, 6, v156
	v_cndmask_b32_e64 v141, v162, v141, s[6:7]
	v_lshlrev_b32_e32 v141, 3, v141
	v_and_or_b32 v141, v141, s60, v155
	v_lshlrev_b32_e32 v157, 3, v141
	global_load_dwordx4 v[158:161], v157, s[70:71]
	global_load_dwordx4 v[164:167], v157, s[70:71] offset:16
	v_pk_mul_f32 v[170:171], v[118:119], v[144:145] op_sel_hi:[1,0]
	v_pk_mul_f32 v[142:143], v[126:127], v[144:145] op_sel_hi:[1,0]
	v_pk_mul_f32 v[172:173], v[116:117], v[144:145] op_sel_hi:[1,0]
	v_pk_mul_f32 v[168:169], v[124:125], v[144:145] op_sel_hi:[1,0]
	s_lshl_b32 s46, s94, 1
	v_mov_b32_e32 v141, v133
	s_mov_b64 s[0:1], 0
	s_waitcnt vmcnt(1)
	v_mov_b32_e32 v178, v159
	s_waitcnt vmcnt(0)
	v_mov_b32_e32 v174, v165
	v_mov_b32_e32 v175, v167
	v_pk_mul_f32 v[176:177], v[170:171], v[174:175]
	v_mov_b32_e32 v179, v161
	v_mov_b32_e32 v165, v166
	v_pk_mul_f32 v[180:181], v[172:173], v[178:179]
	v_pk_fma_f32 v[166:167], v[142:143], v[164:165], v[176:177] neg_lo:[0,0,1] neg_hi:[0,0,1]
	v_mov_b32_e32 v159, v160
	v_pk_mul_f32 v[164:165], v[170:171], v[164:165]
	v_pk_fma_f32 v[160:161], v[168:169], v[158:159], v[180:181] neg_lo:[0,0,1] neg_hi:[0,0,1]
	v_pk_mul_f32 v[158:159], v[172:173], v[158:159]
	v_pk_fma_f32 v[142:143], v[142:143], v[174:175], v[164:165]
	v_lshl_add_u64 v[164:165], v[146:147], 0, s[46:47]
	v_pk_fma_f32 v[158:159], v[168:169], v[178:179], v[158:159]
	v_lshl_add_u64 v[164:165], v[138:139], 1, v[164:165]
	v_lshl_add_u64 v[168:169], v[164:165], 0, v[140:141]
	v_cvt_pk_bf16_f32 v160, v160, v161
	v_cvt_pk_bf16_f32 v161, v166, v167
	v_cvt_pk_bf16_f32 v158, v158, v159
	v_cvt_pk_bf16_f32 v159, v142, v143
	global_store_dwordx2 v[168:169], v[160:161], off offset:128
	global_store_dwordx2 v[168:169], v[158:159], off offset:144
	global_load_dwordx4 v[158:161], v157, s[70:71]
	s_nop 0
	global_load_dwordx4 v[164:167], v157, s[70:71] offset:16
	v_pk_mul_f32 v[172:173], v[114:115], v[144:145] op_sel_hi:[1,0]
	v_pk_mul_f32 v[174:175], v[112:113], v[144:145] op_sel_hi:[1,0]
	v_pk_mul_f32 v[142:143], v[122:123], v[144:145] op_sel_hi:[1,0]
	v_pk_mul_f32 v[170:171], v[120:121], v[144:145] op_sel_hi:[1,0]
	s_waitcnt vmcnt(1)
	v_mov_b32_e32 v180, v159
	s_waitcnt vmcnt(0)
	v_mov_b32_e32 v176, v165
	v_mov_b32_e32 v177, v167
	v_mov_b32_e32 v181, v161
	v_pk_mul_f32 v[178:179], v[172:173], v[176:177]
	v_pk_mul_f32 v[182:183], v[174:175], v[180:181]
	v_mov_b32_e32 v165, v166
	v_mov_b32_e32 v159, v160
	v_pk_fma_f32 v[166:167], v[142:143], v[164:165], v[178:179] neg_lo:[0,0,1] neg_hi:[0,0,1]
	v_pk_fma_f32 v[160:161], v[170:171], v[158:159], v[182:183] neg_lo:[0,0,1] neg_hi:[0,0,1]
	v_pk_mul_f32 v[164:165], v[172:173], v[164:165]
	v_pk_mul_f32 v[158:159], v[174:175], v[158:159]
	v_pk_fma_f32 v[142:143], v[142:143], v[176:177], v[164:165]
	v_pk_fma_f32 v[158:159], v[170:171], v[180:181], v[158:159]
	v_cvt_pk_bf16_f32 v160, v160, v161
	v_cvt_pk_bf16_f32 v161, v166, v167
	v_cvt_pk_bf16_f32 v158, v158, v159
	v_cvt_pk_bf16_f32 v159, v142, v143
	global_store_dwordx2 v[168:169], v[160:161], off offset:896
	global_store_dwordx2 v[168:169], v[158:159], off offset:912

; __device__ __forceinline__ void st4(bf16_t* p, f32x4 v) { u32x2 w; w.x = cvt_pk_bf16(v[0], v[1]); w.y = cvt_pk_bf16(v[2], v[3]); *(u32x2*)p = w; }
;     __device__ __forceinline__ void operator()(const f32x4 (&acc)[2][2][4][2], const Unit& u, int wr, int wc, int fr, int fq) const {
;     ...
;             for (int m = 0; m < 4; ++m) { const int row = row0 + ai * HALF + m * 16; const f32x4 sq = *(const f32x4*)(SSQQ + row * 4);
;                 const float sc = C2M / sqrtf(((sq[0] + sq[1]) + (sq[2] + sq[3])) * (1.f / 256.f) + NEPS);
;                 bf16_t* qrow = QM + (size_t)row * 768;
;                 if (u.pn < 2) {
; #pragma unroll
;                     for (int bj = 0; bj < 2; ++bj)
; #pragma unroll
;                         for (int n = 0; n < 2; ++n) { const int c = u.pn * BM + bj * HALF + wc * 32 + n * 16 + 4 * fq; st4(qrow + (c >> 6) * 96 + (c & 63), acc[ai][bj][m][n] * sc); }
;                 } else {
;                     const int srow = row & (SEQL - 1), prow = srow >> 6, pcol = srow & 63; const int a = fq >> 1, e0 = 4 * (fq & 1), pos = a ? pcol : prow;
; #pragma unroll
;                     for (int bj = 0; bj < 2; ++bj) { f32x4 y1, y2; rope4(acc[ai][bj][m][0] * sc, acc[ai][bj][m][1] * sc, ropeM + (pos * 8 + e0) * 2, y1, y2);
;                         bf16_t* hp = qrow + (4 * bj + wc) * 96 + 64; st4(hp + 16 * a + e0, y1); st4(hp + 16 * a + 8 + e0, y2); }
.LBB0_622:
	v_add_u32_e32 v115, 16, v156
	v_lshlrev_b32_e32 v112, 2, v115
	v_ashrrev_i32_e32 v113, 31, v112
	v_lshl_add_u64 v[112:113], v[112:113], 2, s[16:17]
	v_mov_b64_e32 v[112:113], s[22:23]
	v_mad_i64_i32 v[112:113], s[0:1], v115, s59, v[112:113]
	s_mov_b64 s[10:11], -1
	v_add_f32_e32 v114, v190, v191
	v_add_f32_e32 v116, v192, v193
	v_add_f32_e32 v114, v114, v116
	v_fmamk_f32 v114, v114, 0x3b800000, v153
	v_mul_f32_e32 v116, 0x4f800000, v114
	v_cmp_gt_f32_e32 vcc, s33, v114
	v_cndmask_b32_e64 v117, 0, 1, s[84:85]
	s_nop 0
	v_cndmask_b32_e32 v114, v114, v116, vcc
	v_sqrt_f32_e32 v116, v114
	s_nop 0
	v_add_u32_e32 v118, -1, v116
	v_add_u32_e32 v119, 1, v116
	v_fma_f32 v120, -v118, v116, v114
	v_fma_f32 v121, -v119, v116, v114
	v_cmp_ge_f32_e64 s[0:1], 0, v120
	s_nop 1
	v_cndmask_b32_e64 v116, v116, v118, s[0:1]
	v_cmp_lt_f32_e64 s[0:1], 0, v121
	s_nop 1
	v_cndmask_b32_e64 v116, v116, v119, s[0:1]
	v_mul_f32_e32 v118, 0x37800000, v116
	v_cndmask_b32_e32 v116, v116, v118, vcc
	v_cmp_class_f32_e32 vcc, v114, v154
	s_nop 1
	v_cndmask_b32_e32 v114, v116, v114, vcc
	v_div_scale_f32 v116, s[0:1], v114, v114, s58
	v_rcp_f32_e32 v118, v116
	v_cmp_ne_u32_e64 s[0:1], 1, v117
	v_div_scale_f32 v117, vcc, s58, v114, s58
	v_fma_f32 v119, -v116, v118, 1.0
	v_fmac_f32_e32 v118, v119, v118
	v_mul_f32_e32 v119, v117, v118
	v_fma_f32 v120, -v116, v119, v117
	v_fmac_f32_e32 v119, v120, v118
	v_fma_f32 v116, -v116, v119, v117
	v_div_fmas_f32 v116, v116, v118, v119
	s_andn2_b64 vcc, exec, s[84:85]
	v_div_fixup_f32 v114, v116, v114, s58
	s_cbranch_vccnz .LBB0_624
	v_lshrrev_b32_e32 v116, 6, v115
	v_cndmask_b32_e64 v115, v115, v116, s[6:7]
	v_lshlrev_b32_e32 v115, 3, v115
	v_and_or_b32 v115, v115, s60, v155
	v_pk_mul_f32 v[124:125], v[110:111], v[114:115] op_sel_hi:[1,0]
	v_pk_mul_f32 v[126:127], v[108:109], v[114:115] op_sel_hi:[1,0]
	v_pk_mul_f32 v[146:147], v[102:103], v[114:115] op_sel_hi:[1,0]
	v_pk_mul_f32 v[164:165], v[100:101], v[114:115] op_sel_hi:[1,0]
	v_lshlrev_b32_e32 v115, 3, v115
	global_load_dwordx4 v[116:119], v115, s[70:71]
	global_load_dwordx4 v[120:123], v115, s[70:71] offset:16
	s_lshl_b32 s46, s94, 1
	v_mov_b32_e32 v141, v133
	s_mov_b64 s[10:11], 0
	s_waitcnt vmcnt(1)
	v_mov_b32_e32 v170, v117
	s_waitcnt vmcnt(0)
	v_mov_b32_e32 v166, v121
	v_mov_b32_e32 v167, v123
	v_pk_mul_f32 v[168:169], v[146:147], v[166:167]
	v_mov_b32_e32 v171, v119
	v_mov_b32_e32 v121, v122
	v_pk_mul_f32 v[172:173], v[164:165], v[170:171]
	v_pk_fma_f32 v[122:123], v[124:125], v[120:121], v[168:169] neg_lo:[0,0,1] neg_hi:[0,0,1]
	v_mov_b32_e32 v117, v118
	v_pk_mul_f32 v[120:121], v[146:147], v[120:121]
	v_pk_fma_f32 v[118:119], v[126:127], v[116:117], v[172:173] neg_lo:[0,0,1] neg_hi:[0,0,1]
	v_pk_mul_f32 v[116:117], v[164:165], v[116:117]
	v_pk_fma_f32 v[120:121], v[124:125], v[166:167], v[120:121]
	v_lshl_add_u64 v[124:125], v[112:113], 0, s[46:47]
	v_pk_fma_f32 v[116:117], v[126:127], v[170:171], v[116:117]
	v_lshl_add_u64 v[124:125], v[138:139], 1, v[124:125]
	v_lshl_add_u64 v[124:125], v[124:125], 0, v[140:141]
	v_cvt_pk_bf16_f32 v118, v118, v119
	v_cvt_pk_bf16_f32 v119, v122, v123
	v_cvt_pk_bf16_f32 v116, v116, v117
	v_cvt_pk_bf16_f32 v117, v120, v121
	global_store_dwordx2 v[124:125], v[118:119], off offset:128
	global_store_dwordx2 v[124:125], v[116:117], off offset:144
	global_load_dwordx4 v[116:119], v115, s[70:71]
	s_nop 0
	global_load_dwordx4 v[120:123], v115, s[70:71] offset:16
	v_pk_mul_f32 v[164:165], v[98:99], v[114:115] op_sel_hi:[1,0]
	v_pk_mul_f32 v[166:167], v[96:97], v[114:115] op_sel_hi:[1,0]
	v_pk_mul_f32 v[126:127], v[106:107], v[114:115] op_sel_hi:[1,0]
	v_pk_mul_f32 v[146:147], v[104:105], v[114:115] op_sel_hi:[1,0]
	s_waitcnt vmcnt(1)
	v_mov_b32_e32 v172, v117
	s_waitcnt vmcnt(0)
	v_mov_b32_e32 v168, v121
	v_mov_b32_e32 v169, v123
	v_mov_b32_e32 v173, v119
	v_pk_mul_f32 v[170:171], v[164:165], v[168:169]
	v_pk_mul_f32 v[174:175], v[166:167], v[172:173]
	v_mov_b32_e32 v121, v122
	v_mov_b32_e32 v117, v118
	v_pk_fma_f32 v[122:123], v[126:127], v[120:121], v[170:171] neg_lo:[0,0,1] neg_hi:[0,0,1]
	v_pk_fma_f32 v[118:119], v[146:147], v[116:117], v[174:175] neg_lo:[0,0,1] neg_hi:[0,0,1]
	v_pk_mul_f32 v[120:121], v[164:165], v[120:121]
	v_pk_mul_f32 v[116:117], v[166:167], v[116:117]
	v_pk_fma_f32 v[120:121], v[126:127], v[168:169], v[120:121]
	v_pk_fma_f32 v[116:117], v[146:147], v[172:173], v[116:117]
	v_cvt_pk_bf16_f32 v118, v118, v119
	v_cvt_pk_bf16_f32 v119, v122, v123
	v_cvt_pk_bf16_f32 v116, v116, v117
	v_cvt_pk_bf16_f32 v117, v120, v121
	global_store_dwordx2 v[124:125], v[118:119], off offset:896
	global_store_dwordx2 v[124:125], v[116:117], off offset:912

; __device__ __forceinline__ void st4(bf16_t* p, f32x4 v) { u32x2 w; w.x = cvt_pk_bf16(v[0], v[1]); w.y = cvt_pk_bf16(v[2], v[3]); *(u32x2*)p = w; }
;     __device__ __forceinline__ void operator()(const f32x4 (&acc)[2][2][4][2], const Unit& u, int wr, int wc, int fr, int fq) const {
;     ...
;             for (int m = 0; m < 4; ++m) { const int row = row0 + ai * HALF + m * 16; const f32x4 sq = *(const f32x4*)(SSQQ + row * 4);
;                 const float sc = C2M / sqrtf(((sq[0] + sq[1]) + (sq[2] + sq[3])) * (1.f / 256.f) + NEPS);
;                 bf16_t* qrow = QM + (size_t)row * 768;
;                 if (u.pn < 2) {
; #pragma unroll
;                     for (int bj = 0; bj < 2; ++bj)
; #pragma unroll
;                         for (int n = 0; n < 2; ++n) { const int c = u.pn * BM + bj * HALF + wc * 32 + n * 16 + 4 * fq; st4(qrow + (c >> 6) * 96 + (c & 63), acc[ai][bj][m][n] * sc); }
;                 } else {
;                     const int srow = row & (SEQL - 1), prow = srow >> 6, pcol = srow & 63; const int a = fq >> 1, e0 = 4 * (fq & 1), pos = a ? pcol : prow;
; #pragma unroll
;                     for (int bj = 0; bj < 2; ++bj) { f32x4 y1, y2; rope4(acc[ai][bj][m][0] * sc, acc[ai][bj][m][1] * sc, ropeM + (pos * 8 + e0) * 2, y1, y2);
;                         bf16_t* hp = qrow + (4 * bj + wc) * 96 + 64; st4(hp + 16 * a + e0, y1); st4(hp + 16 * a + 8 + e0, y2); }
.LBB0_626:
	v_add_u32_e32 v97, 32, v156
	v_lshlrev_b32_e32 v98, 2, v97
	v_ashrrev_i32_e32 v99, 31, v98
	v_lshl_add_u64 v[98:99], v[98:99], 2, s[16:17]
	v_add_f32_e32 v96, v194, v195
	v_add_f32_e32 v98, v196, v197
	v_add_f32_e32 v96, v96, v98
	v_fmamk_f32 v96, v96, 0x3b800000, v153
	v_cmp_gt_f32_e32 vcc, s33, v96
	v_mul_f32_e32 v98, 0x4f800000, v96
	s_nop 0
	v_cndmask_b32_e32 v96, v96, v98, vcc
	v_sqrt_f32_e32 v98, v96
	s_nop 0
	v_add_u32_e32 v99, -1, v98
	v_fma_f32 v100, -v99, v98, v96
	v_cmp_ge_f32_e64 s[10:11], 0, v100
	v_add_u32_e32 v100, 1, v98
	s_nop 0
	v_cndmask_b32_e64 v99, v98, v99, s[10:11]
	v_fma_f32 v98, -v100, v98, v96
	v_cmp_lt_f32_e64 s[10:11], 0, v98
	s_nop 1
	v_cndmask_b32_e64 v98, v99, v100, s[10:11]
	v_mul_f32_e32 v99, 0x37800000, v98
	v_cndmask_b32_e32 v98, v98, v99, vcc
	v_cmp_class_f32_e32 vcc, v96, v154
	s_nop 1
	v_cndmask_b32_e32 v96, v98, v96, vcc
	v_div_scale_f32 v98, s[10:11], v96, v96, s58
	v_rcp_f32_e32 v99, v98
	s_nop 0
	v_fma_f32 v100, -v98, v99, 1.0
	v_fmac_f32_e32 v99, v100, v99
	v_div_scale_f32 v100, vcc, s58, v96, s58
	v_mul_f32_e32 v101, v100, v99
	v_fma_f32 v102, -v98, v101, v100
	v_fmac_f32_e32 v101, v102, v99
	v_fma_f32 v98, -v98, v101, v100
	v_div_fmas_f32 v98, v98, v99, v101
	v_div_fixup_f32 v96, v98, v96, s58
	v_mov_b64_e32 v[98:99], s[22:23]
	v_mad_i64_i32 v[98:99], s[10:11], v97, s59, v[98:99]
	s_mov_b64 s[10:11], -1
	s_and_b64 vcc, exec, s[0:1]
	s_cbranch_vccnz .LBB0_628
	v_lshrrev_b32_e32 v100, 6, v97
	v_cndmask_b32_e64 v97, v97, v100, s[6:7]
	v_lshlrev_b32_e32 v97, 3, v97
	v_and_or_b32 v97, v97, s60, v155
	v_pk_mul_f32 v[108:109], v[94:95], v[96:97] op_sel_hi:[1,0]
	v_pk_mul_f32 v[110:111], v[92:93], v[96:97] op_sel_hi:[1,0]
	v_pk_mul_f32 v[112:113], v[86:87], v[96:97] op_sel_hi:[1,0]
	v_pk_mul_f32 v[114:115], v[84:85], v[96:97] op_sel_hi:[1,0]
	v_lshlrev_b32_e32 v97, 3, v97
	global_load_dwordx4 v[100:103], v97, s[70:71]
	global_load_dwordx4 v[104:107], v97, s[70:71] offset:16
	s_lshl_b32 s46, s94, 1
	v_mov_b32_e32 v141, v133
	s_mov_b64 s[10:11], 0
	s_waitcnt vmcnt(1)
	v_mov_b32_e32 v120, v101
	s_waitcnt vmcnt(0)
	v_mov_b32_e32 v116, v105
	v_mov_b32_e32 v117, v107
	v_pk_mul_f32 v[118:119], v[112:113], v[116:117]
	v_mov_b32_e32 v121, v103
	v_mov_b32_e32 v105, v106
	v_pk_mul_f32 v[122:123], v[114:115], v[120:121]
	v_pk_fma_f32 v[106:107], v[108:109], v[104:105], v[118:119] neg_lo:[0,0,1] neg_hi:[0,0,1]
	v_mov_b32_e32 v101, v102
	v_pk_mul_f32 v[104:105], v[112:113], v[104:105]
	v_pk_fma_f32 v[102:103], v[110:111], v[100:101], v[122:123] neg_lo:[0,0,1] neg_hi:[0,0,1]
	v_pk_mul_f32 v[100:101], v[114:115], v[100:101]
	v_pk_fma_f32 v[104:105], v[108:109], v[116:117], v[104:105]
	v_lshl_add_u64 v[108:109], v[98:99], 0, s[46:47]
	v_pk_fma_f32 v[100:101], v[110:111], v[120:121], v[100:101]
	v_lshl_add_u64 v[108:109], v[138:139], 1, v[108:109]
	v_lshl_add_u64 v[108:109], v[108:109], 0, v[140:141]
	v_cvt_pk_bf16_f32 v102, v102, v103
	v_cvt_pk_bf16_f32 v103, v106, v107
	v_cvt_pk_bf16_f32 v100, v100, v101
	v_cvt_pk_bf16_f32 v101, v104, v105
	global_store_dwordx2 v[108:109], v[102:103], off offset:128
	global_store_dwordx2 v[108:109], v[100:101], off offset:144
	global_load_dwordx4 v[100:103], v97, s[70:71]
	s_nop 0
	global_load_dwordx4 v[104:107], v97, s[70:71] offset:16
	v_pk_mul_f32 v[114:115], v[82:83], v[96:97] op_sel_hi:[1,0]
	v_pk_mul_f32 v[116:117], v[80:81], v[96:97] op_sel_hi:[1,0]
	v_pk_mul_f32 v[110:111], v[90:91], v[96:97] op_sel_hi:[1,0]
	v_pk_mul_f32 v[112:113], v[88:89], v[96:97] op_sel_hi:[1,0]
	s_waitcnt vmcnt(1)
	v_mov_b32_e32 v122, v101
	s_waitcnt vmcnt(0)
	v_mov_b32_e32 v118, v105
	v_mov_b32_e32 v119, v107
	v_mov_b32_e32 v123, v103
	v_pk_mul_f32 v[120:121], v[114:115], v[118:119]
	v_pk_mul_f32 v[124:125], v[116:117], v[122:123]
	v_mov_b32_e32 v105, v106
	v_mov_b32_e32 v101, v102
	v_pk_fma_f32 v[106:107], v[110:111], v[104:105], v[120:121] neg_lo:[0,0,1] neg_hi:[0,0,1]
	v_pk_fma_f32 v[102:103], v[112:113], v[100:101], v[124:125] neg_lo:[0,0,1] neg_hi:[0,0,1]
	v_pk_mul_f32 v[104:105], v[114:115], v[104:105]
	v_pk_mul_f32 v[100:101], v[116:117], v[100:101]
	v_pk_fma_f32 v[104:105], v[110:111], v[118:119], v[104:105]
	v_pk_fma_f32 v[100:101], v[112:113], v[122:123], v[100:101]
	v_cvt_pk_bf16_f32 v102, v102, v103
	v_cvt_pk_bf16_f32 v103, v106, v107
	v_cvt_pk_bf16_f32 v100, v100, v101
	v_cvt_pk_bf16_f32 v101, v104, v105
	global_store_dwordx2 v[108:109], v[102:103], off offset:896
	global_store_dwordx2 v[108:109], v[100:101], off offset:912

; __device__ __forceinline__ void st4(bf16_t* p, f32x4 v) { u32x2 w; w.x = cvt_pk_bf16(v[0], v[1]); w.y = cvt_pk_bf16(v[2], v[3]); *(u32x2*)p = w; }
;     __device__ __forceinline__ void operator()(const f32x4 (&acc)[2][2][4][2], const Unit& u, int wr, int wc, int fr, int fq) const {
;     ...
;             for (int m = 0; m < 4; ++m) { const int row = row0 + ai * HALF + m * 16; const f32x4 sq = *(const f32x4*)(SSQQ + row * 4);
;                 const float sc = C2M / sqrtf(((sq[0] + sq[1]) + (sq[2] + sq[3])) * (1.f / 256.f) + NEPS);
;                 bf16_t* qrow = QM + (size_t)row * 768;
;                 if (u.pn < 2) {
; #pragma unroll
;                     for (int bj = 0; bj < 2; ++bj)
; #pragma unroll
;                         for (int n = 0; n < 2; ++n) { const int c = u.pn * BM + bj * HALF + wc * 32 + n * 16 + 4 * fq; st4(qrow + (c >> 6) * 96 + (c & 63), acc[ai][bj][m][n] * sc); }
;                 } else {
;                     const int srow = row & (SEQL - 1), prow = srow >> 6, pcol = srow & 63; const int a = fq >> 1, e0 = 4 * (fq & 1), pos = a ? pcol : prow;
; #pragma unroll
;                     for (int bj = 0; bj < 2; ++bj) { f32x4 y1, y2; rope4(acc[ai][bj][m][0] * sc, acc[ai][bj][m][1] * sc, ropeM + (pos * 8 + e0) * 2, y1, y2);
;                         bf16_t* hp = qrow + (4 * bj + wc) * 96 + 64; st4(hp + 16 * a + e0, y1); st4(hp + 16 * a + 8 + e0, y2); }
.LBB0_630:
	v_add_u32_e32 v81, 48, v156
	v_lshlrev_b32_e32 v82, 2, v81
	v_ashrrev_i32_e32 v83, 31, v82
	v_lshl_add_u64 v[82:83], v[82:83], 2, s[16:17]
	v_add_f32_e32 v80, v198, v199
	v_add_f32_e32 v82, v200, v201
	v_add_f32_e32 v80, v80, v82
	v_fmamk_f32 v80, v80, 0x3b800000, v153
	v_cmp_gt_f32_e32 vcc, s33, v80
	v_mul_f32_e32 v82, 0x4f800000, v80
	s_nop 0
	v_cndmask_b32_e32 v80, v80, v82, vcc
	v_sqrt_f32_e32 v82, v80
	s_nop 0
	v_add_u32_e32 v83, -1, v82
	v_fma_f32 v84, -v83, v82, v80
	v_cmp_ge_f32_e64 s[10:11], 0, v84
	v_add_u32_e32 v84, 1, v82
	s_nop 0
	v_cndmask_b32_e64 v83, v82, v83, s[10:11]
	v_fma_f32 v82, -v84, v82, v80
	v_cmp_lt_f32_e64 s[10:11], 0, v82
	s_nop 1
	v_cndmask_b32_e64 v82, v83, v84, s[10:11]
	v_mul_f32_e32 v83, 0x37800000, v82
	v_cndmask_b32_e32 v82, v82, v83, vcc
	v_cmp_class_f32_e32 vcc, v80, v154
	s_nop 1
	v_cndmask_b32_e32 v80, v82, v80, vcc
	v_div_scale_f32 v82, s[10:11], v80, v80, s58
	v_rcp_f32_e32 v83, v82
	s_nop 0
	v_fma_f32 v84, -v82, v83, 1.0
	v_fmac_f32_e32 v83, v84, v83
	v_div_scale_f32 v84, vcc, s58, v80, s58
	v_mul_f32_e32 v85, v84, v83
	v_fma_f32 v86, -v82, v85, v84
	v_fmac_f32_e32 v85, v86, v83
	v_fma_f32 v82, -v82, v85, v84
	v_div_fmas_f32 v82, v82, v83, v85
	v_div_fixup_f32 v80, v82, v80, s58
	v_mov_b64_e32 v[82:83], s[22:23]
	v_mad_i64_i32 v[82:83], s[10:11], v81, s59, v[82:83]
	s_mov_b64 s[10:11], -1
	s_and_b64 vcc, exec, s[0:1]
	s_cbranch_vccnz .LBB0_632
	v_lshrrev_b32_e32 v84, 6, v81
	v_cndmask_b32_e64 v81, v81, v84, s[6:7]
	v_lshlrev_b32_e32 v81, 3, v81
	v_and_or_b32 v81, v81, s60, v155
	v_pk_mul_f32 v[92:93], v[78:79], v[80:81] op_sel_hi:[1,0]
	v_pk_mul_f32 v[94:95], v[76:77], v[80:81] op_sel_hi:[1,0]
	v_pk_mul_f32 v[96:97], v[70:71], v[80:81] op_sel_hi:[1,0]
	v_pk_mul_f32 v[98:99], v[68:69], v[80:81] op_sel_hi:[1,0]
	v_lshlrev_b32_e32 v81, 3, v81
	global_load_dwordx4 v[84:87], v81, s[70:71]
	global_load_dwordx4 v[88:91], v81, s[70:71] offset:16
	s_lshl_b32 s46, s94, 1
	v_mov_b32_e32 v141, v133
	s_mov_b64 s[10:11], 0
	s_waitcnt vmcnt(1)
	v_mov_b32_e32 v104, v85
	s_waitcnt vmcnt(0)
	v_mov_b32_e32 v100, v89
	v_mov_b32_e32 v101, v91
	v_pk_mul_f32 v[102:103], v[96:97], v[100:101]
	v_mov_b32_e32 v105, v87
	v_mov_b32_e32 v89, v90
	v_pk_mul_f32 v[106:107], v[98:99], v[104:105]
	v_pk_fma_f32 v[90:91], v[92:93], v[88:89], v[102:103] neg_lo:[0,0,1] neg_hi:[0,0,1]
	v_mov_b32_e32 v85, v86
	v_pk_mul_f32 v[88:89], v[96:97], v[88:89]
	v_pk_fma_f32 v[86:87], v[94:95], v[84:85], v[106:107] neg_lo:[0,0,1] neg_hi:[0,0,1]
	v_pk_mul_f32 v[84:85], v[98:99], v[84:85]
	v_pk_fma_f32 v[88:89], v[92:93], v[100:101], v[88:89]
	v_lshl_add_u64 v[92:93], v[82:83], 0, s[46:47]
	v_pk_fma_f32 v[84:85], v[94:95], v[104:105], v[84:85]
	v_lshl_add_u64 v[92:93], v[138:139], 1, v[92:93]
	v_lshl_add_u64 v[92:93], v[92:93], 0, v[140:141]
	v_cvt_pk_bf16_f32 v86, v86, v87
	v_cvt_pk_bf16_f32 v87, v90, v91
	v_cvt_pk_bf16_f32 v84, v84, v85
	v_cvt_pk_bf16_f32 v85, v88, v89
	global_store_dwordx2 v[92:93], v[86:87], off offset:128
	global_store_dwordx2 v[92:93], v[84:85], off offset:144
	global_load_dwordx4 v[84:87], v81, s[70:71]
	s_nop 0
	global_load_dwordx4 v[88:91], v81, s[70:71] offset:16
	v_pk_mul_f32 v[98:99], v[66:67], v[80:81] op_sel_hi:[1,0]
	v_pk_mul_f32 v[100:101], v[64:65], v[80:81] op_sel_hi:[1,0]
	v_pk_mul_f32 v[94:95], v[74:75], v[80:81] op_sel_hi:[1,0]
	v_pk_mul_f32 v[96:97], v[72:73], v[80:81] op_sel_hi:[1,0]
	s_waitcnt vmcnt(1)
	v_mov_b32_e32 v106, v85
	s_waitcnt vmcnt(0)
	v_mov_b32_e32 v102, v89
	v_mov_b32_e32 v103, v91
	v_mov_b32_e32 v107, v87
	v_pk_mul_f32 v[104:105], v[98:99], v[102:103]
	v_pk_mul_f32 v[108:109], v[100:101], v[106:107]
	v_mov_b32_e32 v89, v90
	v_mov_b32_e32 v85, v86
	v_pk_fma_f32 v[90:91], v[94:95], v[88:89], v[104:105] neg_lo:[0,0,1] neg_hi:[0,0,1]
	v_pk_fma_f32 v[86:87], v[96:97], v[84:85], v[108:109] neg_lo:[0,0,1] neg_hi:[0,0,1]
	v_pk_mul_f32 v[88:89], v[98:99], v[88:89]
	v_pk_mul_f32 v[84:85], v[100:101], v[84:85]
	v_pk_fma_f32 v[88:89], v[94:95], v[102:103], v[88:89]
	v_pk_fma_f32 v[84:85], v[96:97], v[106:107], v[84:85]
	v_cvt_pk_bf16_f32 v86, v86, v87
	v_cvt_pk_bf16_f32 v87, v90, v91
	v_cvt_pk_bf16_f32 v84, v84, v85
	v_cvt_pk_bf16_f32 v85, v88, v89
	global_store_dwordx2 v[92:93], v[86:87], off offset:896
	global_store_dwordx2 v[92:93], v[84:85], off offset:912

; __device__ __forceinline__ void st4(bf16_t* p, f32x4 v) { u32x2 w; w.x = cvt_pk_bf16(v[0], v[1]); w.y = cvt_pk_bf16(v[2], v[3]); *(u32x2*)p = w; }
;     __device__ __forceinline__ void operator()(const f32x4 (&acc)[2][2][4][2], const Unit& u, int wr, int wc, int fr, int fq) const {
;     ...
;             for (int m = 0; m < 4; ++m) { const int row = row0 + ai * HALF + m * 16; const f32x4 sq = *(const f32x4*)(SSQQ + row * 4);
;                 const float sc = C2M / sqrtf(((sq[0] + sq[1]) + (sq[2] + sq[3])) * (1.f / 256.f) + NEPS);
;                 bf16_t* qrow = QM + (size_t)row * 768;
;                 if (u.pn < 2) {
; #pragma unroll
;                     for (int bj = 0; bj < 2; ++bj)
; #pragma unroll
;                         for (int n = 0; n < 2; ++n) { const int c = u.pn * BM + bj * HALF + wc * 32 + n * 16 + 4 * fq; st4(qrow + (c >> 6) * 96 + (c & 63), acc[ai][bj][m][n] * sc); }
;                 } else {
;                     const int srow = row & (SEQL - 1), prow = srow >> 6, pcol = srow & 63; const int a = fq >> 1, e0 = 4 * (fq & 1), pos = a ? pcol : prow;
; #pragma unroll
;                     for (int bj = 0; bj < 2; ++bj) { f32x4 y1, y2; rope4(acc[ai][bj][m][0] * sc, acc[ai][bj][m][1] * sc, ropeM + (pos * 8 + e0) * 2, y1, y2);
;                         bf16_t* hp = qrow + (4 * bj + wc) * 96 + 64; st4(hp + 16 * a + e0, y1); st4(hp + 16 * a + 8 + e0, y2); }
.LBB0_634:
	v_add_u32_e32 v65, 0x80, v156
	v_lshlrev_b32_e32 v66, 2, v65
	v_ashrrev_i32_e32 v67, 31, v66
	v_lshl_add_u64 v[66:67], v[66:67], 2, s[16:17]
	v_add_f32_e32 v64, v202, v203
	v_add_f32_e32 v66, v204, v205
	v_add_f32_e32 v64, v64, v66
	v_fmamk_f32 v64, v64, 0x3b800000, v153
	v_cmp_gt_f32_e32 vcc, s33, v64
	v_mul_f32_e32 v66, 0x4f800000, v64
	s_nop 0
	v_cndmask_b32_e32 v64, v64, v66, vcc
	v_sqrt_f32_e32 v66, v64
	s_nop 0
	v_add_u32_e32 v67, -1, v66
	v_fma_f32 v68, -v67, v66, v64
	v_cmp_ge_f32_e64 s[10:11], 0, v68
	v_add_u32_e32 v68, 1, v66
	s_nop 0
	v_cndmask_b32_e64 v67, v66, v67, s[10:11]
	v_fma_f32 v66, -v68, v66, v64
	v_cmp_lt_f32_e64 s[10:11], 0, v66
	s_nop 1
	v_cndmask_b32_e64 v66, v67, v68, s[10:11]
	v_mul_f32_e32 v67, 0x37800000, v66
	v_cndmask_b32_e32 v66, v66, v67, vcc
	v_cmp_class_f32_e32 vcc, v64, v154
	s_nop 1
	v_cndmask_b32_e32 v64, v66, v64, vcc
	v_div_scale_f32 v66, s[10:11], v64, v64, s58
	v_rcp_f32_e32 v67, v66
	s_nop 0
	v_fma_f32 v68, -v66, v67, 1.0
	v_fmac_f32_e32 v67, v68, v67
	v_div_scale_f32 v68, vcc, s58, v64, s58
	v_mul_f32_e32 v69, v68, v67
	v_fma_f32 v70, -v66, v69, v68
	v_fmac_f32_e32 v69, v70, v67
	v_fma_f32 v66, -v66, v69, v68
	v_div_fmas_f32 v66, v66, v67, v69
	v_div_fixup_f32 v64, v66, v64, s58
	v_mov_b64_e32 v[66:67], s[22:23]
	v_mad_i64_i32 v[66:67], s[10:11], v65, s59, v[66:67]
	s_mov_b64 s[10:11], -1
	s_and_b64 vcc, exec, s[0:1]
	s_cbranch_vccnz .LBB0_636
	v_lshrrev_b32_e32 v65, 6, v65
	v_cndmask_b32_e64 v65, v162, v65, s[6:7]
	v_lshlrev_b32_e32 v65, 3, v65
	v_and_or_b32 v65, v65, s60, v155
	v_pk_mul_f32 v[76:77], v[62:63], v[64:65] op_sel_hi:[1,0]
	v_pk_mul_f32 v[78:79], v[60:61], v[64:65] op_sel_hi:[1,0]
	v_pk_mul_f32 v[80:81], v[54:55], v[64:65] op_sel_hi:[1,0]
	v_pk_mul_f32 v[82:83], v[52:53], v[64:65] op_sel_hi:[1,0]
	v_lshlrev_b32_e32 v65, 3, v65
	global_load_dwordx4 v[68:71], v65, s[70:71]
	global_load_dwordx4 v[72:75], v65, s[70:71] offset:16
	s_lshl_b32 s46, s94, 1
	v_mov_b32_e32 v141, v133
	s_mov_b64 s[10:11], 0
	s_waitcnt vmcnt(1)
	v_mov_b32_e32 v88, v69
	s_waitcnt vmcnt(0)
	v_mov_b32_e32 v84, v73
	v_mov_b32_e32 v85, v75
	v_pk_mul_f32 v[86:87], v[80:81], v[84:85]
	v_mov_b32_e32 v89, v71
	v_mov_b32_e32 v73, v74
	v_pk_mul_f32 v[90:91], v[82:83], v[88:89]
	v_pk_fma_f32 v[74:75], v[76:77], v[72:73], v[86:87] neg_lo:[0,0,1] neg_hi:[0,0,1]
	v_mov_b32_e32 v69, v70
	v_pk_mul_f32 v[72:73], v[80:81], v[72:73]
	v_pk_fma_f32 v[70:71], v[78:79], v[68:69], v[90:91] neg_lo:[0,0,1] neg_hi:[0,0,1]
	v_pk_mul_f32 v[68:69], v[82:83], v[68:69]
	v_pk_fma_f32 v[72:73], v[76:77], v[84:85], v[72:73]
	v_lshl_add_u64 v[76:77], v[66:67], 0, s[46:47]
	v_pk_fma_f32 v[68:69], v[78:79], v[88:89], v[68:69]
	v_lshl_add_u64 v[76:77], v[138:139], 1, v[76:77]
	v_lshl_add_u64 v[76:77], v[76:77], 0, v[140:141]
	v_cvt_pk_bf16_f32 v70, v70, v71
	v_cvt_pk_bf16_f32 v71, v74, v75
	v_cvt_pk_bf16_f32 v68, v68, v69
	v_cvt_pk_bf16_f32 v69, v72, v73
	global_store_dwordx2 v[76:77], v[70:71], off offset:128
	global_store_dwordx2 v[76:77], v[68:69], off offset:144
	global_load_dwordx4 v[68:71], v65, s[70:71]
	s_nop 0
	global_load_dwordx4 v[72:75], v65, s[70:71] offset:16
	v_pk_mul_f32 v[82:83], v[50:51], v[64:65] op_sel_hi:[1,0]
	v_pk_mul_f32 v[84:85], v[48:49], v[64:65] op_sel_hi:[1,0]
	v_pk_mul_f32 v[78:79], v[58:59], v[64:65] op_sel_hi:[1,0]
	v_pk_mul_f32 v[80:81], v[56:57], v[64:65] op_sel_hi:[1,0]
	s_waitcnt vmcnt(1)
	v_mov_b32_e32 v90, v69
	s_waitcnt vmcnt(0)
	v_mov_b32_e32 v86, v73
	v_mov_b32_e32 v87, v75
	v_mov_b32_e32 v91, v71
	v_pk_mul_f32 v[88:89], v[82:83], v[86:87]
	v_pk_mul_f32 v[92:93], v[84:85], v[90:91]
	v_mov_b32_e32 v73, v74
	v_mov_b32_e32 v69, v70
	v_pk_fma_f32 v[74:75], v[78:79], v[72:73], v[88:89] neg_lo:[0,0,1] neg_hi:[0,0,1]
	v_pk_fma_f32 v[70:71], v[80:81], v[68:69], v[92:93] neg_lo:[0,0,1] neg_hi:[0,0,1]
	v_pk_mul_f32 v[72:73], v[82:83], v[72:73]
	v_pk_mul_f32 v[68:69], v[84:85], v[68:69]
	v_pk_fma_f32 v[72:73], v[78:79], v[86:87], v[72:73]
	v_pk_fma_f32 v[68:69], v[80:81], v[90:91], v[68:69]
	v_cvt_pk_bf16_f32 v70, v70, v71
	v_cvt_pk_bf16_f32 v71, v74, v75
	v_cvt_pk_bf16_f32 v68, v68, v69
	v_cvt_pk_bf16_f32 v69, v72, v73
	global_store_dwordx2 v[76:77], v[70:71], off offset:896
	global_store_dwordx2 v[76:77], v[68:69], off offset:912

; __device__ __forceinline__ void st4(bf16_t* p, f32x4 v) { u32x2 w; w.x = cvt_pk_bf16(v[0], v[1]); w.y = cvt_pk_bf16(v[2], v[3]); *(u32x2*)p = w; }
;     __device__ __forceinline__ void operator()(const f32x4 (&acc)[2][2][4][2], const Unit& u, int wr, int wc, int fr, int fq) const {
;     ...
;             for (int m = 0; m < 4; ++m) { const int row = row0 + ai * HALF + m * 16; const f32x4 sq = *(const f32x4*)(SSQQ + row * 4);
;                 const float sc = C2M / sqrtf(((sq[0] + sq[1]) + (sq[2] + sq[3])) * (1.f / 256.f) + NEPS);
;                 bf16_t* qrow = QM + (size_t)row * 768;
;                 if (u.pn < 2) {
; #pragma unroll
;                     for (int bj = 0; bj < 2; ++bj)
; #pragma unroll
;                         for (int n = 0; n < 2; ++n) { const int c = u.pn * BM + bj * HALF + wc * 32 + n * 16 + 4 * fq; st4(qrow + (c >> 6) * 96 + (c & 63), acc[ai][bj][m][n] * sc); }
;                 } else {
;                     const int srow = row & (SEQL - 1), prow = srow >> 6, pcol = srow & 63; const int a = fq >> 1, e0 = 4 * (fq & 1), pos = a ? pcol : prow;
; #pragma unroll
;                     for (int bj = 0; bj < 2; ++bj) { f32x4 y1, y2; rope4(acc[ai][bj][m][0] * sc, acc[ai][bj][m][1] * sc, ropeM + (pos * 8 + e0) * 2, y1, y2);
;                         bf16_t* hp = qrow + (4 * bj + wc) * 96 + 64; st4(hp + 16 * a + e0, y1); st4(hp + 16 * a + 8 + e0, y2); }
.LBB0_638:
	v_add_u32_e32 v49, 0x90, v156
	v_lshlrev_b32_e32 v50, 2, v49
	v_ashrrev_i32_e32 v51, 31, v50
	v_lshl_add_u64 v[50:51], v[50:51], 2, s[16:17]
	v_add_f32_e32 v48, v206, v207
	v_add_f32_e32 v50, v208, v209
	v_add_f32_e32 v48, v48, v50
	v_fmamk_f32 v48, v48, 0x3b800000, v153
	v_cmp_gt_f32_e32 vcc, s33, v48
	v_mul_f32_e32 v50, 0x4f800000, v48
	s_nop 0
	v_cndmask_b32_e32 v48, v48, v50, vcc
	v_sqrt_f32_e32 v50, v48
	s_nop 0
	v_add_u32_e32 v51, -1, v50
	v_fma_f32 v52, -v51, v50, v48
	v_cmp_ge_f32_e64 s[10:11], 0, v52
	v_add_u32_e32 v52, 1, v50
	s_nop 0
	v_cndmask_b32_e64 v51, v50, v51, s[10:11]
	v_fma_f32 v50, -v52, v50, v48
	v_cmp_lt_f32_e64 s[10:11], 0, v50
	s_nop 1
	v_cndmask_b32_e64 v50, v51, v52, s[10:11]
	v_mul_f32_e32 v51, 0x37800000, v50
	v_cndmask_b32_e32 v50, v50, v51, vcc
	v_cmp_class_f32_e32 vcc, v48, v154
	s_nop 1
	v_cndmask_b32_e32 v48, v50, v48, vcc
	v_div_scale_f32 v50, s[10:11], v48, v48, s58
	v_rcp_f32_e32 v51, v50
	s_nop 0
	v_fma_f32 v52, -v50, v51, 1.0
	v_fmac_f32_e32 v51, v52, v51
	v_div_scale_f32 v52, vcc, s58, v48, s58
	v_mul_f32_e32 v53, v52, v51
	v_fma_f32 v54, -v50, v53, v52
	v_fmac_f32_e32 v53, v54, v51
	v_fma_f32 v50, -v50, v53, v52
	v_div_fmas_f32 v50, v50, v51, v53
	v_div_fixup_f32 v48, v50, v48, s58
	v_mov_b64_e32 v[50:51], s[22:23]
	v_mad_i64_i32 v[50:51], s[10:11], v49, s59, v[50:51]
	s_mov_b64 s[10:11], -1
	s_and_b64 vcc, exec, s[0:1]
	s_cbranch_vccnz .LBB0_640
	v_lshrrev_b32_e32 v52, 6, v49
	v_cndmask_b32_e64 v49, v49, v52, s[6:7]
	v_lshlrev_b32_e32 v49, 3, v49
	v_and_or_b32 v49, v49, s60, v155
	v_pk_mul_f32 v[60:61], v[46:47], v[48:49] op_sel_hi:[1,0]
	v_pk_mul_f32 v[62:63], v[44:45], v[48:49] op_sel_hi:[1,0]
	v_pk_mul_f32 v[64:65], v[38:39], v[48:49] op_sel_hi:[1,0]
	v_pk_mul_f32 v[66:67], v[36:37], v[48:49] op_sel_hi:[1,0]
	v_lshlrev_b32_e32 v49, 3, v49
	global_load_dwordx4 v[52:55], v49, s[70:71]
	global_load_dwordx4 v[56:59], v49, s[70:71] offset:16
	s_lshl_b32 s46, s94, 1
	v_mov_b32_e32 v141, v133
	s_mov_b64 s[10:11], 0
	s_waitcnt vmcnt(1)
	v_mov_b32_e32 v72, v53
	s_waitcnt vmcnt(0)
	v_mov_b32_e32 v68, v57
	v_mov_b32_e32 v69, v59
	v_pk_mul_f32 v[70:71], v[64:65], v[68:69]
	v_mov_b32_e32 v73, v55
	v_mov_b32_e32 v57, v58
	v_pk_mul_f32 v[74:75], v[66:67], v[72:73]
	v_pk_fma_f32 v[58:59], v[60:61], v[56:57], v[70:71] neg_lo:[0,0,1] neg_hi:[0,0,1]
	v_mov_b32_e32 v53, v54
	v_pk_mul_f32 v[56:57], v[64:65], v[56:57]
	v_pk_fma_f32 v[54:55], v[62:63], v[52:53], v[74:75] neg_lo:[0,0,1] neg_hi:[0,0,1]
	v_pk_mul_f32 v[52:53], v[66:67], v[52:53]
	v_pk_fma_f32 v[56:57], v[60:61], v[68:69], v[56:57]
	v_lshl_add_u64 v[60:61], v[50:51], 0, s[46:47]
	v_pk_fma_f32 v[52:53], v[62:63], v[72:73], v[52:53]
	v_lshl_add_u64 v[60:61], v[138:139], 1, v[60:61]
	v_lshl_add_u64 v[60:61], v[60:61], 0, v[140:141]
	v_cvt_pk_bf16_f32 v54, v54, v55
	v_cvt_pk_bf16_f32 v55, v58, v59
	v_cvt_pk_bf16_f32 v52, v52, v53
	v_cvt_pk_bf16_f32 v53, v56, v57
	global_store_dwordx2 v[60:61], v[54:55], off offset:128
	global_store_dwordx2 v[60:61], v[52:53], off offset:144
	global_load_dwordx4 v[52:55], v49, s[70:71]
	s_nop 0
	global_load_dwordx4 v[56:59], v49, s[70:71] offset:16
	v_pk_mul_f32 v[66:67], v[34:35], v[48:49] op_sel_hi:[1,0]
	v_pk_mul_f32 v[68:69], v[32:33], v[48:49] op_sel_hi:[1,0]
	v_pk_mul_f32 v[62:63], v[42:43], v[48:49] op_sel_hi:[1,0]
	v_pk_mul_f32 v[64:65], v[40:41], v[48:49] op_sel_hi:[1,0]
	s_waitcnt vmcnt(1)
	v_mov_b32_e32 v74, v53
	s_waitcnt vmcnt(0)
	v_mov_b32_e32 v70, v57
	v_mov_b32_e32 v71, v59
	v_mov_b32_e32 v75, v55
	v_pk_mul_f32 v[72:73], v[66:67], v[70:71]
	v_pk_mul_f32 v[76:77], v[68:69], v[74:75]
	v_mov_b32_e32 v57, v58
	v_mov_b32_e32 v53, v54
	v_pk_fma_f32 v[58:59], v[62:63], v[56:57], v[72:73] neg_lo:[0,0,1] neg_hi:[0,0,1]
	v_pk_fma_f32 v[54:55], v[64:65], v[52:53], v[76:77] neg_lo:[0,0,1] neg_hi:[0,0,1]
	v_pk_mul_f32 v[56:57], v[66:67], v[56:57]
	v_pk_mul_f32 v[52:53], v[68:69], v[52:53]
	v_pk_fma_f32 v[56:57], v[62:63], v[70:71], v[56:57]
	v_pk_fma_f32 v[52:53], v[64:65], v[74:75], v[52:53]
	v_cvt_pk_bf16_f32 v54, v54, v55
	v_cvt_pk_bf16_f32 v55, v58, v59
	v_cvt_pk_bf16_f32 v52, v52, v53
	v_cvt_pk_bf16_f32 v53, v56, v57
	global_store_dwordx2 v[60:61], v[54:55], off offset:896
	global_store_dwordx2 v[60:61], v[52:53], off offset:912

; __device__ __forceinline__ void st4(bf16_t* p, f32x4 v) { u32x2 w; w.x = cvt_pk_bf16(v[0], v[1]); w.y = cvt_pk_bf16(v[2], v[3]); *(u32x2*)p = w; }
;     __device__ __forceinline__ void operator()(const f32x4 (&acc)[2][2][4][2], const Unit& u, int wr, int wc, int fr, int fq) const {
;     ...
;             for (int m = 0; m < 4; ++m) { const int row = row0 + ai * HALF + m * 16; const f32x4 sq = *(const f32x4*)(SSQQ + row * 4);
;                 const float sc = C2M / sqrtf(((sq[0] + sq[1]) + (sq[2] + sq[3])) * (1.f / 256.f) + NEPS);
;                 bf16_t* qrow = QM + (size_t)row * 768;
;                 if (u.pn < 2) {
; #pragma unroll
;                     for (int bj = 0; bj < 2; ++bj)
; #pragma unroll
;                         for (int n = 0; n < 2; ++n) { const int c = u.pn * BM + bj * HALF + wc * 32 + n * 16 + 4 * fq; st4(qrow + (c >> 6) * 96 + (c & 63), acc[ai][bj][m][n] * sc); }
;                 } else {
;                     const int srow = row & (SEQL - 1), prow = srow >> 6, pcol = srow & 63; const int a = fq >> 1, e0 = 4 * (fq & 1), pos = a ? pcol : prow;
; #pragma unroll
;                     for (int bj = 0; bj < 2; ++bj) { f32x4 y1, y2; rope4(acc[ai][bj][m][0] * sc, acc[ai][bj][m][1] * sc, ropeM + (pos * 8 + e0) * 2, y1, y2);
;                         bf16_t* hp = qrow + (4 * bj + wc) * 96 + 64; st4(hp + 16 * a + e0, y1); st4(hp + 16 * a + 8 + e0, y2); }
.LBB0_642:
	v_add_u32_e32 v33, 0xa0, v156
	v_lshlrev_b32_e32 v34, 2, v33
	v_ashrrev_i32_e32 v35, 31, v34
	v_lshl_add_u64 v[34:35], v[34:35], 2, s[16:17]
	v_add_f32_e32 v32, v210, v211
	v_add_f32_e32 v34, v212, v213
	v_add_f32_e32 v32, v32, v34
	v_fmamk_f32 v32, v32, 0x3b800000, v153
	v_cmp_gt_f32_e32 vcc, s33, v32
	v_mul_f32_e32 v34, 0x4f800000, v32
	s_nop 0
	v_cndmask_b32_e32 v32, v32, v34, vcc
	v_sqrt_f32_e32 v34, v32
	s_nop 0
	v_add_u32_e32 v35, -1, v34
	v_fma_f32 v36, -v35, v34, v32
	v_cmp_ge_f32_e64 s[10:11], 0, v36
	v_add_u32_e32 v36, 1, v34
	s_nop 0
	v_cndmask_b32_e64 v35, v34, v35, s[10:11]
	v_fma_f32 v34, -v36, v34, v32
	v_cmp_lt_f32_e64 s[10:11], 0, v34
	s_nop 1
	v_cndmask_b32_e64 v34, v35, v36, s[10:11]
	v_mul_f32_e32 v35, 0x37800000, v34
	v_cndmask_b32_e32 v34, v34, v35, vcc
	v_cmp_class_f32_e32 vcc, v32, v154
	s_nop 1
	v_cndmask_b32_e32 v32, v34, v32, vcc
	v_div_scale_f32 v34, s[10:11], v32, v32, s58
	v_rcp_f32_e32 v35, v34
	s_nop 0
	v_fma_f32 v36, -v34, v35, 1.0
	v_fmac_f32_e32 v35, v36, v35
	v_div_scale_f32 v36, vcc, s58, v32, s58
	v_mul_f32_e32 v37, v36, v35
	v_fma_f32 v38, -v34, v37, v36
	v_fmac_f32_e32 v37, v38, v35
	v_fma_f32 v34, -v34, v37, v36
	v_div_fmas_f32 v34, v34, v35, v37
	v_div_fixup_f32 v32, v34, v32, s58
	v_mov_b64_e32 v[34:35], s[22:23]
	v_mad_i64_i32 v[34:35], s[10:11], v33, s59, v[34:35]
	s_mov_b64 s[10:11], -1
	s_and_b64 vcc, exec, s[0:1]
	s_cbranch_vccnz .LBB0_644
	v_lshrrev_b32_e32 v36, 6, v33
	v_cndmask_b32_e64 v33, v33, v36, s[6:7]
	v_lshlrev_b32_e32 v33, 3, v33
	v_and_or_b32 v33, v33, s60, v155
	v_pk_mul_f32 v[44:45], v[30:31], v[32:33] op_sel_hi:[1,0]
	v_pk_mul_f32 v[46:47], v[28:29], v[32:33] op_sel_hi:[1,0]
	v_pk_mul_f32 v[48:49], v[22:23], v[32:33] op_sel_hi:[1,0]
	v_pk_mul_f32 v[50:51], v[20:21], v[32:33] op_sel_hi:[1,0]
	v_lshlrev_b32_e32 v33, 3, v33
	global_load_dwordx4 v[36:39], v33, s[70:71]
	global_load_dwordx4 v[40:43], v33, s[70:71] offset:16
	s_lshl_b32 s46, s94, 1
	v_mov_b32_e32 v141, v133
	s_mov_b64 s[10:11], 0
	s_waitcnt vmcnt(1)
	v_mov_b32_e32 v56, v37
	s_waitcnt vmcnt(0)
	v_mov_b32_e32 v52, v41
	v_mov_b32_e32 v53, v43
	v_pk_mul_f32 v[54:55], v[48:49], v[52:53]
	v_mov_b32_e32 v57, v39
	v_mov_b32_e32 v41, v42
	v_pk_mul_f32 v[58:59], v[50:51], v[56:57]
	v_pk_fma_f32 v[42:43], v[44:45], v[40:41], v[54:55] neg_lo:[0,0,1] neg_hi:[0,0,1]
	v_mov_b32_e32 v37, v38
	v_pk_mul_f32 v[40:41], v[48:49], v[40:41]
	v_pk_fma_f32 v[38:39], v[46:47], v[36:37], v[58:59] neg_lo:[0,0,1] neg_hi:[0,0,1]
	v_pk_mul_f32 v[36:37], v[50:51], v[36:37]
	v_pk_fma_f32 v[40:41], v[44:45], v[52:53], v[40:41]
	v_lshl_add_u64 v[44:45], v[34:35], 0, s[46:47]
	v_pk_fma_f32 v[36:37], v[46:47], v[56:57], v[36:37]
	v_lshl_add_u64 v[44:45], v[138:139], 1, v[44:45]
	v_lshl_add_u64 v[44:45], v[44:45], 0, v[140:141]
	v_cvt_pk_bf16_f32 v38, v38, v39
	v_cvt_pk_bf16_f32 v39, v42, v43
	v_cvt_pk_bf16_f32 v36, v36, v37
	v_cvt_pk_bf16_f32 v37, v40, v41
	global_store_dwordx2 v[44:45], v[38:39], off offset:128
	global_store_dwordx2 v[44:45], v[36:37], off offset:144
	global_load_dwordx4 v[36:39], v33, s[70:71]
	s_nop 0
	global_load_dwordx4 v[40:43], v33, s[70:71] offset:16
	v_pk_mul_f32 v[50:51], v[18:19], v[32:33] op_sel_hi:[1,0]
	v_pk_mul_f32 v[52:53], v[16:17], v[32:33] op_sel_hi:[1,0]
	v_pk_mul_f32 v[46:47], v[26:27], v[32:33] op_sel_hi:[1,0]
	v_pk_mul_f32 v[48:49], v[24:25], v[32:33] op_sel_hi:[1,0]
	s_waitcnt vmcnt(1)
	v_mov_b32_e32 v58, v37
	s_waitcnt vmcnt(0)
	v_mov_b32_e32 v54, v41
	v_mov_b32_e32 v55, v43
	v_mov_b32_e32 v59, v39
	v_pk_mul_f32 v[56:57], v[50:51], v[54:55]
	v_pk_mul_f32 v[60:61], v[52:53], v[58:59]
	v_mov_b32_e32 v41, v42
	v_mov_b32_e32 v37, v38
	v_pk_fma_f32 v[42:43], v[46:47], v[40:41], v[56:57] neg_lo:[0,0,1] neg_hi:[0,0,1]
	v_pk_fma_f32 v[38:39], v[48:49], v[36:37], v[60:61] neg_lo:[0,0,1] neg_hi:[0,0,1]
	v_pk_mul_f32 v[40:41], v[50:51], v[40:41]
	v_pk_mul_f32 v[36:37], v[52:53], v[36:37]
	v_pk_fma_f32 v[40:41], v[46:47], v[54:55], v[40:41]
	v_pk_fma_f32 v[36:37], v[48:49], v[58:59], v[36:37]
	v_cvt_pk_bf16_f32 v38, v38, v39
	v_cvt_pk_bf16_f32 v39, v42, v43
	v_cvt_pk_bf16_f32 v36, v36, v37
	v_cvt_pk_bf16_f32 v37, v40, v41
	global_store_dwordx2 v[44:45], v[38:39], off offset:896
	global_store_dwordx2 v[44:45], v[36:37], off offset:912

;     __device__ __forceinline__ void operator()(const f32x4 (&acc)[2][2][4][2], const Unit& u, int wr, int wc, int fr, int fq) const {
;     ...
;             for (int m = 0; m < 4; ++m) { const int row = row0 + ai * HALF + m * 16; const f32x4 sq = *(const f32x4*)(SSQQ + row * 4);
;                 const float sc = C2M / sqrtf(((sq[0] + sq[1]) + (sq[2] + sq[3])) * (1.f / 256.f) + NEPS);
;                 bf16_t* qrow = QM + (size_t)row * 768;
;                 if (u.pn < 2) {
.LBB0_646:
	v_add_u32_e32 v17, 0xb0, v156
	v_lshlrev_b32_e32 v18, 2, v17
	v_ashrrev_i32_e32 v19, 31, v18
	v_lshl_add_u64 v[18:19], v[18:19], 2, s[16:17]
	v_add_f32_e32 v16, v214, v215
	v_add_f32_e32 v18, v216, v217
	v_add_f32_e32 v16, v16, v18
	v_fmamk_f32 v16, v16, 0x3b800000, v153
	v_cmp_gt_f32_e32 vcc, s33, v16
	v_mul_f32_e32 v18, 0x4f800000, v16
	s_nop 0
	v_cndmask_b32_e32 v16, v16, v18, vcc
	v_sqrt_f32_e32 v18, v16
	s_nop 0
	v_add_u32_e32 v19, -1, v18
	v_fma_f32 v20, -v19, v18, v16
	v_cmp_ge_f32_e64 s[10:11], 0, v20
	v_add_u32_e32 v20, 1, v18
	s_nop 0
	v_cndmask_b32_e64 v19, v18, v19, s[10:11]
	v_fma_f32 v18, -v20, v18, v16
	v_cmp_lt_f32_e64 s[10:11], 0, v18
	s_nop 1
	v_cndmask_b32_e64 v18, v19, v20, s[10:11]
	v_mul_f32_e32 v19, 0x37800000, v18
	v_cndmask_b32_e32 v18, v18, v19, vcc
	v_cmp_class_f32_e32 vcc, v16, v154
	s_nop 1
	v_cndmask_b32_e32 v16, v18, v16, vcc
	v_div_scale_f32 v18, s[10:11], v16, v16, s58
	v_rcp_f32_e32 v19, v18
	s_nop 0
	v_fma_f32 v20, -v18, v19, 1.0
	v_fmac_f32_e32 v19, v20, v19
	v_div_scale_f32 v20, vcc, s58, v16, s58
	v_mul_f32_e32 v21, v20, v19
	v_fma_f32 v22, -v18, v21, v20
	v_fmac_f32_e32 v21, v22, v19
	v_fma_f32 v18, -v18, v21, v20
	v_div_fmas_f32 v18, v18, v19, v21
	v_div_fixup_f32 v16, v18, v16, s58
	v_mov_b64_e32 v[18:19], s[22:23]
	v_mad_i64_i32 v[18:19], s[10:11], v17, s59, v[18:19]
	s_mov_b64 s[10:11], -1
	s_and_b64 vcc, exec, s[0:1]
	s_cbranch_vccz .LBB0_649
	s_andn2_b64 vcc, exec, s[10:11]
	s_cbranch_vccz .LBB0_650

;     __device__ __forceinline__ void operator()(const f32x4 (&acc)[2][2][4][2], const Unit& u, int wr, int wc, int fr, int fq) const {
;     ...
;             for (int m = 0; m < 4; ++m) { const int row = row0 + ai * HALF + m * 16; const f32x4 sq = *(const f32x4*)(SSQKV + row * 4);
;                 const float sc = 1.0f / sqrtf(((sq[0] + sq[1]) + (sq[2] + sq[3])) * (1.f / 128.f) + NEPS);
;                 if (u.pn < 2) {
.LBB0_674:
	s_lshl_b32 s7, s10, 8
	v_mov_b32_e32 v132, v142
	v_mov_b32_e32 v166, v141
	s_add_i32 s7, s7, s36
	s_cmp_gt_i32 s6, 1
	v_add_u32_e32 v161, s7, v166
	v_lshlrev_b32_e32 v138, 2, v161
	v_ashrrev_i32_e32 v139, 31, v138
	v_lshl_add_u64 v[138:139], v[138:139], 2, s[14:15]
	global_load_dwordx4 v[210:213], v[138:139], off offset:256
	global_load_dwordx4 v[214:217], v[138:139], off offset:512
	global_load_dwordx4 v[218:221], v[138:139], off offset:768
	global_load_dwordx4 v[222:225], v[138:139], off offset:2048
	global_load_dwordx4 v[226:229], v[138:139], off offset:2304
	global_load_dwordx4 v[230:233], v[138:139], off offset:2560
	global_load_dwordx4 v[234:237], v[138:139], off offset:2816
	global_load_dwordx4 v[154:157], v[138:139], off
	s_cselect_b64 s[74:75], -1, 0
	s_lshl_b32 s63, s6, 8
	v_lshlrev_b32_e32 v138, 2, v132
	v_ashrrev_i32_e32 v139, 9, v161
	s_add_i32 s7, s61, s63
	v_and_b32_e32 v168, -8, v139
	v_add_u32_e32 v139, s7, v138
	v_add_u32_e32 v140, 16, v139
	v_add_u32_e32 v153, 0x80, v139
	s_cmp_lt_i32 s6, 2
	v_and_b32_e32 v167, 63, v166
	v_ashrrev_i32_e32 v159, 6, v139
	v_and_b32_e32 v152, 60, v139
	v_add_u32_e32 v139, 0x90, v139
	s_mov_b64 s[10:11], -1
	v_lshlrev_b32_e32 v132, 1, v167
	v_or_b32_e32 v151, 1, v152
	v_or_b32_e32 v150, 2, v152
	v_or_b32_e32 v149, 3, v152
	s_waitcnt vmcnt(0)
	v_add_f32_e32 v154, v154, v155
	v_add_f32_e32 v155, v156, v157
	v_add_f32_e32 v154, v154, v155
	v_fmamk_f32 v154, v154, 0x3c000000, v147
	v_mul_f32_e32 v155, 0x4f800000, v154
	v_cmp_gt_f32_e32 vcc, s69, v154
	v_ashrrev_i32_e32 v157, 6, v140
	v_and_b32_e32 v156, 60, v140
	v_cndmask_b32_e32 v154, v154, v155, vcc
	v_sqrt_f32_e32 v158, v154
	v_ashrrev_i32_e32 v155, 6, v153
	v_add_u32_e32 v140, -1, v158
	v_add_u32_e32 v153, 1, v158
	v_fma_f32 v160, -v140, v158, v154
	v_fma_f32 v162, -v153, v158, v154
	v_cmp_ge_f32_e64 s[6:7], 0, v160
	s_nop 1
	v_cndmask_b32_e64 v140, v158, v140, s[6:7]
	v_cmp_lt_f32_e64 s[6:7], 0, v162
	s_nop 1
	v_cndmask_b32_e64 v140, v140, v153, s[6:7]
	v_mul_f32_e32 v153, 0x37800000, v140
	v_cndmask_b32_e32 v140, v140, v153, vcc
	v_cmp_class_f32_e32 vcc, v154, v148
	v_ashrrev_i32_e32 v153, 6, v139
	s_nop 0
	v_cndmask_b32_e32 v140, v140, v154, vcc
	v_div_scale_f32 v154, s[6:7], v140, v140, 1.0
	v_rcp_f32_e32 v158, v154
	v_div_scale_f32 v160, vcc, 1.0, v140, 1.0
	v_fma_f32 v162, -v154, v158, 1.0
	v_fmac_f32_e32 v158, v162, v158
	v_mul_f32_e32 v162, v160, v158
	v_fma_f32 v163, -v154, v162, v160
	v_fmac_f32_e32 v162, v163, v158
	v_fma_f32 v154, -v154, v162, v160
	v_div_fmas_f32 v154, v154, v158, v162
	v_div_fixup_f32 v140, v154, v140, 1.0
	v_and_b32_e32 v154, 60, v139
	s_cbranch_scc1 .LBB0_676
; __device__ __forceinline__ unsigned short bf1(float v) { return (unsigned short)(cvt_pk_bf16(v, 0.f) & 0xffffu); }
;     __device__ __forceinline__ void operator()(const f32x4 (&acc)[2][2][4][2], const Unit& u, int wr, int wc, int fr, int fq) const {
;     ...
;                     for (int bj = 0; bj < 2; ++bj)
; #pragma unroll
;                         for (int n = 0; n < 2; ++n)
; #pragma unroll
;                             for (int i = 0; i < 4; ++i) { const int c = (u.pn - 2) * BM + bj * HALF + wc * 32 + n * 16 + 4 * fq + i; VTM[((((size_t)((row >> 12) * 8 + (c >> 6)) * 64 + ((row & (SEQL - 1)) >> 6)) * 64 + (c & 63)) * 64) + (row & 63)] = bf1(acc[ai][bj][m][n][i] * sc); }
	v_add_u32_e32 v164, v159, v168
	v_ashrrev_i32_e32 v165, 31, v164
	v_and_b32_e32 v139, 0xfc0, v161
	v_lshlrev_b64 v[164:165], 12, v[164:165]
	v_or_b32_e32 v158, v164, v139
	v_or_b32_e32 v164, v158, v152
	v_lshl_add_u64 v[162:163], s[52:53], 0, v[132:133]
	v_mul_f32_e32 v160, v124, v140
	v_lshlrev_b64 v[170:171], 7, v[164:165]
	v_cvt_pk_bf16_f32 v160, v160, s0
	v_lshl_add_u64 v[170:171], v[162:163], 0, v[170:171]
	v_or_b32_e32 v164, v158, v151
	global_store_short v[170:171], v160, off
	v_mul_f32_e32 v160, v125, v140
	v_lshlrev_b64 v[170:171], 7, v[164:165]
	v_cvt_pk_bf16_f32 v160, v160, s0
	v_lshl_add_u64 v[170:171], v[162:163], 0, v[170:171]
	v_or_b32_e32 v164, v158, v150
	global_store_short v[170:171], v160, off
	v_mul_f32_e32 v160, v126, v140
	v_lshlrev_b64 v[170:171], 7, v[164:165]
	v_cvt_pk_bf16_f32 v160, v160, s0
	v_lshl_add_u64 v[170:171], v[162:163], 0, v[170:171]
	v_or_b32_e32 v164, v158, v149
	global_store_short v[170:171], v160, off
	v_mul_f32_e32 v160, v127, v140
	v_lshlrev_b64 v[164:165], 7, v[164:165]
	v_cvt_pk_bf16_f32 v160, v160, s0
	v_lshl_add_u64 v[164:165], v[162:163], 0, v[164:165]
	global_store_short v[164:165], v160, off
	v_add_u32_e32 v164, v157, v168
	v_ashrrev_i32_e32 v165, 31, v164
	v_lshlrev_b64 v[164:165], 12, v[164:165]
	v_or3_b32 v164, v164, v139, v156
	v_mul_f32_e32 v158, v120, v140
	v_lshlrev_b64 v[170:171], 7, v[164:165]
	v_cvt_pk_bf16_f32 v158, v158, s0
	v_lshl_add_u64 v[170:171], v[162:163], 0, v[170:171]
	global_store_short v[170:171], v158, off
	v_or_b32_e32 v170, 1, v164
	v_mov_b32_e32 v171, v165
	v_mul_f32_e32 v158, v121, v140
	v_lshlrev_b64 v[170:171], 7, v[170:171]
	v_cvt_pk_bf16_f32 v158, v158, s0
	v_lshl_add_u64 v[170:171], v[162:163], 0, v[170:171]
	global_store_short v[170:171], v158, off
	v_or_b32_e32 v170, 2, v164
	v_mov_b32_e32 v171, v165
	v_mul_f32_e32 v158, v122, v140
	v_lshlrev_b64 v[170:171], 7, v[170:171]
	v_cvt_pk_bf16_f32 v158, v158, s0
	v_lshl_add_u64 v[170:171], v[162:163], 0, v[170:171]
	v_or_b32_e32 v164, 3, v164
	global_store_short v[170:171], v158, off
	v_mul_f32_e32 v158, v123, v140
	v_lshlrev_b64 v[164:165], 7, v[164:165]
	v_cvt_pk_bf16_f32 v158, v158, s0
	v_lshl_add_u64 v[164:165], v[162:163], 0, v[164:165]
	global_store_short v[164:165], v158, off
	v_add_u32_e32 v164, v155, v168
	v_ashrrev_i32_e32 v165, 31, v164
	v_lshlrev_b64 v[164:165], 12, v[164:165]
	v_or_b32_e32 v158, v164, v139
	v_or_b32_e32 v164, v158, v152
	v_mul_f32_e32 v160, v116, v140
	v_lshlrev_b64 v[170:171], 7, v[164:165]
	v_cvt_pk_bf16_f32 v160, v160, s0
	v_lshl_add_u64 v[170:171], v[162:163], 0, v[170:171]
	v_or_b32_e32 v164, v158, v151
	global_store_short v[170:171], v160, off
	v_mul_f32_e32 v160, v117, v140
	v_lshlrev_b64 v[170:171], 7, v[164:165]
	v_cvt_pk_bf16_f32 v160, v160, s0
	v_lshl_add_u64 v[170:171], v[162:163], 0, v[170:171]
	v_or_b32_e32 v164, v158, v150
	global_store_short v[170:171], v160, off
	v_mul_f32_e32 v160, v118, v140
	v_lshlrev_b64 v[170:171], 7, v[164:165]
	v_cvt_pk_bf16_f32 v160, v160, s0
	v_lshl_add_u64 v[170:171], v[162:163], 0, v[170:171]
	v_or_b32_e32 v164, v158, v149
	global_store_short v[170:171], v160, off
	v_mul_f32_e32 v160, v119, v140
	v_lshlrev_b64 v[164:165], 7, v[164:165]
	v_cvt_pk_bf16_f32 v160, v160, s0
	v_lshl_add_u64 v[164:165], v[162:163], 0, v[164:165]
	global_store_short v[164:165], v160, off
	v_add_u32_e32 v164, v153, v168
	v_ashrrev_i32_e32 v165, 31, v164
	v_lshlrev_b64 v[164:165], 12, v[164:165]
	v_or3_b32 v164, v164, v139, v154
	v_mul_f32_e32 v158, v112, v140
	v_lshlrev_b64 v[170:171], 7, v[164:165]
	v_cvt_pk_bf16_f32 v158, v158, s0
	v_lshl_add_u64 v[170:171], v[162:163], 0, v[170:171]
	global_store_short v[170:171], v158, off
	v_or_b32_e32 v170, 1, v164
	v_mov_b32_e32 v171, v165
	v_mul_f32_e32 v139, v113, v140
	v_lshlrev_b64 v[170:171], 7, v[170:171]
	v_cvt_pk_bf16_f32 v139, v139, s0
	v_lshl_add_u64 v[170:171], v[162:163], 0, v[170:171]
	global_store_short v[170:171], v139, off
	v_or_b32_e32 v170, 2, v164
	v_mov_b32_e32 v171, v165
	v_mul_f32_e32 v139, v114, v140
	v_lshlrev_b64 v[170:171], 7, v[170:171]
	v_cvt_pk_bf16_f32 v139, v139, s0
	v_lshl_add_u64 v[170:171], v[162:163], 0, v[170:171]
	v_or_b32_e32 v164, 3, v164
	global_store_short v[170:171], v139, off
	v_mul_f32_e32 v139, v115, v140
	v_lshlrev_b64 v[164:165], 7, v[164:165]
	v_cvt_pk_bf16_f32 v139, v139, s0
	v_lshl_add_u64 v[162:163], v[162:163], 0, v[164:165]
	s_mov_b64 s[10:11], 0
	global_store_short v[162:163], v139, off

; __device__ __forceinline__ unsigned short bf1(float v) { return (unsigned short)(cvt_pk_bf16(v, 0.f) & 0xffffu); }
; __device__ __forceinline__ void st4(bf16_t* p, f32x4 v) { u32x2 w; w.x = cvt_pk_bf16(v[0], v[1]); w.y = cvt_pk_bf16(v[2], v[3]); *(u32x2*)p = w; }
;     __device__ __forceinline__ void operator()(const f32x4 (&acc)[2][2][4][2], const Unit& u, int wr, int wc, int fr, int fq) const {
;     ...
;             for (int m = 0; m < 4; ++m) { const int row = row0 + ai * HALF + m * 16; const f32x4 sq = *(const f32x4*)(SSQKV + row * 4);
;                 const float sc = 1.0f / sqrtf(((sq[0] + sq[1]) + (sq[2] + sq[3])) * (1.f / 128.f) + NEPS);
;                 if (u.pn < 2) {
; #pragma unroll
;                     for (int bj = 0; bj < 2; ++bj)
; #pragma unroll
;                         for (int n = 0; n < 2; ++n) { const int c = u.pn * BM + bj * HALF + wc * 32 + n * 16 + 4 * fq; st4(KN + ((((size_t)((row >> 12) * 8 + (c >> 6)) * 64 + ((row & (SEQL - 1)) >> 6)) * 64 + (row & 63)) * 64) + (c & 63), acc[ai][bj][m][n] * sc); }
;                 } else {
; #pragma unroll
;                     for (int bj = 0; bj < 2; ++bj)
; #pragma unroll
;                         for (int n = 0; n < 2; ++n)
; #pragma unroll
;                             for (int i = 0; i < 4; ++i) { const int c = (u.pn - 2) * BM + bj * HALF + wc * 32 + n * 16 + 4 * fq + i; VTM[((((size_t)((row >> 12) * 8 + (c >> 6)) * 64 + ((row & (SEQL - 1)) >> 6)) * 64 + (c & 63)) * 64) + (row & 63)] = bf1(acc[ai][bj][m][n][i] * sc); }
.LBB0_678:
	v_add_u32_e32 v115, 16, v161
	v_lshlrev_b32_e32 v112, 2, v115
	v_ashrrev_i32_e32 v113, 31, v112
	v_lshl_add_u64 v[112:113], v[112:113], 2, s[14:15]
	v_cndmask_b32_e64 v113, 0, 1, s[74:75]
	v_cmp_ne_u32_e64 s[6:7], 1, v113
	v_add_u32_e32 v112, 16, v166
	v_and_b32_e32 v112, 63, v112
	s_mov_b64 s[76:77], -1
	v_lshlrev_b32_e32 v112, 1, v112
	v_add_f32_e32 v114, v210, v211
	v_add_f32_e32 v116, v212, v213
	v_add_f32_e32 v114, v114, v116
	v_fmamk_f32 v114, v114, 0x3c000000, v147
	v_mul_f32_e32 v116, 0x4f800000, v114
	v_cmp_gt_f32_e32 vcc, s69, v114
	v_ashrrev_i32_e32 v117, 9, v115
	s_nop 0
	v_cndmask_b32_e32 v114, v114, v116, vcc
	v_sqrt_f32_e32 v116, v114
	s_nop 0
	v_add_u32_e32 v113, -1, v116
	v_add_u32_e32 v118, 1, v116
	v_fma_f32 v119, -v113, v116, v114
	v_fma_f32 v120, -v118, v116, v114
	v_cmp_ge_f32_e64 s[10:11], 0, v119
	s_nop 1
	v_cndmask_b32_e64 v113, v116, v113, s[10:11]
	v_cmp_lt_f32_e64 s[10:11], 0, v120
	s_nop 1
	v_cndmask_b32_e64 v113, v113, v118, s[10:11]
	v_mul_f32_e32 v116, 0x37800000, v113
	v_cndmask_b32_e32 v113, v113, v116, vcc
	v_cmp_class_f32_e32 vcc, v114, v148
	v_and_b32_e32 v116, -8, v117
	s_nop 0
	v_cndmask_b32_e32 v113, v113, v114, vcc
	v_div_scale_f32 v114, s[10:11], v113, v113, 1.0
	v_rcp_f32_e32 v118, v114
	v_div_scale_f32 v117, vcc, 1.0, v113, 1.0
	v_fma_f32 v119, -v114, v118, 1.0
	v_fmac_f32_e32 v118, v119, v118
	v_mul_f32_e32 v119, v117, v118
	v_fma_f32 v120, -v114, v119, v117
	v_fmac_f32_e32 v119, v120, v118
	v_fma_f32 v114, -v114, v119, v117
	v_div_fmas_f32 v114, v114, v118, v119
	s_andn2_b64 vcc, exec, s[74:75]
	v_div_fixup_f32 v114, v114, v113, 1.0
	s_cbranch_vccnz .LBB0_680
	v_add_u32_e32 v120, v116, v159
	v_ashrrev_i32_e32 v121, 31, v120
	v_and_b32_e32 v117, 0xfc0, v115
	v_mov_b32_e32 v113, v133
	v_lshlrev_b64 v[120:121], 12, v[120:121]
	v_lshl_add_u64 v[118:119], s[52:53], 0, v[112:113]
	v_or_b32_e32 v113, v120, v117
	v_mul_f32_e32 v120, v108, v114
	v_cvt_pk_bf16_f32 v124, v120, s0
	v_or_b32_e32 v120, v113, v152
	v_lshlrev_b64 v[122:123], 7, v[120:121]
	v_lshl_add_u64 v[122:123], v[118:119], 0, v[122:123]
	v_mul_f32_e32 v120, v109, v114
	global_store_short v[122:123], v124, off
	v_cvt_pk_bf16_f32 v124, v120, s0
	v_or_b32_e32 v120, v113, v151
	v_lshlrev_b64 v[122:123], 7, v[120:121]
	v_lshl_add_u64 v[122:123], v[118:119], 0, v[122:123]
	v_mul_f32_e32 v120, v110, v114
	global_store_short v[122:123], v124, off
	v_cvt_pk_bf16_f32 v124, v120, s0
	v_or_b32_e32 v120, v113, v150
	v_lshlrev_b64 v[122:123], 7, v[120:121]
	v_lshl_add_u64 v[122:123], v[118:119], 0, v[122:123]
	v_mul_f32_e32 v120, v111, v114
	global_store_short v[122:123], v124, off
	v_cvt_pk_bf16_f32 v122, v120, s0
	v_or_b32_e32 v120, v113, v149
	v_lshlrev_b64 v[120:121], 7, v[120:121]
	v_lshl_add_u64 v[120:121], v[118:119], 0, v[120:121]
	global_store_short v[120:121], v122, off
	v_add_u32_e32 v120, v157, v116
	v_ashrrev_i32_e32 v121, 31, v120
	v_lshlrev_b64 v[120:121], 12, v[120:121]
	v_or3_b32 v120, v120, v117, v156
	v_mul_f32_e32 v113, v104, v114
	v_lshlrev_b64 v[122:123], 7, v[120:121]
	v_cvt_pk_bf16_f32 v113, v113, s0
	v_lshl_add_u64 v[122:123], v[118:119], 0, v[122:123]
	global_store_short v[122:123], v113, off
	v_or_b32_e32 v122, 1, v120
	v_mov_b32_e32 v123, v121
	v_mul_f32_e32 v113, v105, v114
	v_lshlrev_b64 v[122:123], 7, v[122:123]
	v_cvt_pk_bf16_f32 v113, v113, s0
	v_lshl_add_u64 v[122:123], v[118:119], 0, v[122:123]
	global_store_short v[122:123], v113, off
	v_or_b32_e32 v122, 2, v120
	v_mov_b32_e32 v123, v121
	v_mul_f32_e32 v113, v106, v114
	v_lshlrev_b64 v[122:123], 7, v[122:123]
	v_cvt_pk_bf16_f32 v113, v113, s0
	v_lshl_add_u64 v[122:123], v[118:119], 0, v[122:123]
	v_or_b32_e32 v120, 3, v120
	global_store_short v[122:123], v113, off
	v_mul_f32_e32 v113, v107, v114
	v_lshlrev_b64 v[120:121], 7, v[120:121]
	v_cvt_pk_bf16_f32 v113, v113, s0
	v_lshl_add_u64 v[120:121], v[118:119], 0, v[120:121]
	global_store_short v[120:121], v113, off
	v_add_u32_e32 v120, v155, v116
	v_ashrrev_i32_e32 v121, 31, v120
	v_lshlrev_b64 v[120:121], 12, v[120:121]
	v_or_b32_e32 v113, v120, v117
	v_mul_f32_e32 v120, v100, v114
	v_cvt_pk_bf16_f32 v124, v120, s0
	v_or_b32_e32 v120, v113, v152
	v_lshlrev_b64 v[122:123], 7, v[120:121]
	v_lshl_add_u64 v[122:123], v[118:119], 0, v[122:123]
	v_mul_f32_e32 v120, v101, v114
	global_store_short v[122:123], v124, off
	v_cvt_pk_bf16_f32 v124, v120, s0
	v_or_b32_e32 v120, v113, v151
	v_lshlrev_b64 v[122:123], 7, v[120:121]
	v_lshl_add_u64 v[122:123], v[118:119], 0, v[122:123]
	v_mul_f32_e32 v120, v102, v114
	global_store_short v[122:123], v124, off
	v_cvt_pk_bf16_f32 v124, v120, s0
	v_or_b32_e32 v120, v113, v150
	v_lshlrev_b64 v[122:123], 7, v[120:121]
	v_lshl_add_u64 v[122:123], v[118:119], 0, v[122:123]
	v_mul_f32_e32 v120, v103, v114
	global_store_short v[122:123], v124, off
	v_cvt_pk_bf16_f32 v122, v120, s0
	v_or_b32_e32 v120, v113, v149
	v_lshlrev_b64 v[120:121], 7, v[120:121]
	v_lshl_add_u64 v[120:121], v[118:119], 0, v[120:121]
	global_store_short v[120:121], v122, off
	v_add_u32_e32 v120, v153, v116
	v_ashrrev_i32_e32 v121, 31, v120
	v_lshlrev_b64 v[120:121], 12, v[120:121]
	v_or3_b32 v120, v120, v117, v154
	v_mul_f32_e32 v113, v96, v114
	v_lshlrev_b64 v[122:123], 7, v[120:121]
	v_cvt_pk_bf16_f32 v113, v113, s0
	v_lshl_add_u64 v[122:123], v[118:119], 0, v[122:123]
	global_store_short v[122:123], v113, off
	v_or_b32_e32 v122, 1, v120
	v_mov_b32_e32 v123, v121
	v_mul_f32_e32 v113, v97, v114
	v_lshlrev_b64 v[122:123], 7, v[122:123]
	v_cvt_pk_bf16_f32 v113, v113, s0
	v_lshl_add_u64 v[122:123], v[118:119], 0, v[122:123]
	global_store_short v[122:123], v113, off
	v_or_b32_e32 v122, 2, v120
	v_mov_b32_e32 v123, v121
	v_mul_f32_e32 v113, v98, v114
	v_lshlrev_b64 v[122:123], 7, v[122:123]
	v_cvt_pk_bf16_f32 v113, v113, s0
	v_lshl_add_u64 v[122:123], v[118:119], 0, v[122:123]
	v_or_b32_e32 v120, 3, v120
	global_store_short v[122:123], v113, off
	v_mul_f32_e32 v113, v99, v114
	v_lshlrev_b64 v[120:121], 7, v[120:121]
	v_cvt_pk_bf16_f32 v113, v113, s0
	v_lshl_add_u64 v[118:119], v[118:119], 0, v[120:121]
	s_mov_b64 s[76:77], 0
	global_store_short v[118:119], v113, off

; __device__ __forceinline__ unsigned short bf1(float v) { return (unsigned short)(cvt_pk_bf16(v, 0.f) & 0xffffu); }
; __device__ __forceinline__ void st4(bf16_t* p, f32x4 v) { u32x2 w; w.x = cvt_pk_bf16(v[0], v[1]); w.y = cvt_pk_bf16(v[2], v[3]); *(u32x2*)p = w; }
;     __device__ __forceinline__ void operator()(const f32x4 (&acc)[2][2][4][2], const Unit& u, int wr, int wc, int fr, int fq) const {
;     ...
;             for (int m = 0; m < 4; ++m) { const int row = row0 + ai * HALF + m * 16; const f32x4 sq = *(const f32x4*)(SSQKV + row * 4);
;                 const float sc = 1.0f / sqrtf(((sq[0] + sq[1]) + (sq[2] + sq[3])) * (1.f / 128.f) + NEPS);
;                 if (u.pn < 2) {
; #pragma unroll
;                     for (int bj = 0; bj < 2; ++bj)
; #pragma unroll
;                         for (int n = 0; n < 2; ++n) { const int c = u.pn * BM + bj * HALF + wc * 32 + n * 16 + 4 * fq; st4(KN + ((((size_t)((row >> 12) * 8 + (c >> 6)) * 64 + ((row & (SEQL - 1)) >> 6)) * 64 + (row & 63)) * 64) + (c & 63), acc[ai][bj][m][n] * sc); }
;                 } else {
; #pragma unroll
;                     for (int bj = 0; bj < 2; ++bj)
; #pragma unroll
;                         for (int n = 0; n < 2; ++n)
; #pragma unroll
;                             for (int i = 0; i < 4; ++i) { const int c = (u.pn - 2) * BM + bj * HALF + wc * 32 + n * 16 + 4 * fq + i; VTM[((((size_t)((row >> 12) * 8 + (c >> 6)) * 64 + ((row & (SEQL - 1)) >> 6)) * 64 + (c & 63)) * 64) + (row & 63)] = bf1(acc[ai][bj][m][n][i] * sc); }
.LBB0_682:
	v_add_u32_e32 v99, 32, v161
	v_lshlrev_b32_e32 v96, 2, v99
	v_ashrrev_i32_e32 v97, 31, v96
	v_lshl_add_u64 v[96:97], v[96:97], 2, s[14:15]
	v_ashrrev_i32_e32 v98, 9, v99
	s_mov_b64 s[74:75], -1
	v_add_f32_e32 v96, v214, v215
	v_add_f32_e32 v97, v216, v217
	v_add_f32_e32 v96, v96, v97
	v_fmamk_f32 v96, v96, 0x3c000000, v147
	v_mul_f32_e32 v97, 0x4f800000, v96
	v_cmp_gt_f32_e32 vcc, s69, v96
	v_xor_b32_e32 v101, 32, v167
	s_nop 0
	v_cndmask_b32_e32 v96, v96, v97, vcc
	v_sqrt_f32_e32 v97, v96
	s_nop 0
	v_add_u32_e32 v100, -1, v97
	v_add_u32_e32 v102, 1, v97
	v_fma_f32 v103, -v100, v97, v96
	v_fma_f32 v104, -v102, v97, v96
	v_cmp_ge_f32_e64 s[10:11], 0, v103
	s_nop 1
	v_cndmask_b32_e64 v97, v97, v100, s[10:11]
	v_cmp_lt_f32_e64 s[10:11], 0, v104
	s_nop 1
	v_cndmask_b32_e64 v97, v97, v102, s[10:11]
	v_mul_f32_e32 v100, 0x37800000, v97
	v_cndmask_b32_e32 v97, v97, v100, vcc
	v_cmp_class_f32_e32 vcc, v96, v148
	v_and_b32_e32 v100, -8, v98
	s_nop 0
	v_cndmask_b32_e32 v96, v97, v96, vcc
	v_div_scale_f32 v97, s[10:11], v96, v96, 1.0
	v_rcp_f32_e32 v102, v97
	v_div_scale_f32 v98, vcc, 1.0, v96, 1.0
	v_fma_f32 v103, -v97, v102, 1.0
	v_fmac_f32_e32 v102, v103, v102
	v_mul_f32_e32 v103, v98, v102
	v_fma_f32 v104, -v97, v103, v98
	v_fmac_f32_e32 v103, v104, v102
	v_fma_f32 v97, -v97, v103, v98
	v_div_fmas_f32 v97, v97, v102, v103
	s_and_b64 vcc, exec, s[6:7]
	v_div_fixup_f32 v98, v97, v96, 1.0
	v_lshlrev_b32_e32 v96, 1, v101
	s_cbranch_vccnz .LBB0_684
	v_add_u32_e32 v104, v100, v159
	v_ashrrev_i32_e32 v105, 31, v104
	v_and_b32_e32 v101, 0xfc0, v99
	v_mov_b32_e32 v97, v133
	v_lshlrev_b64 v[104:105], 12, v[104:105]
	v_lshl_add_u64 v[102:103], s[52:53], 0, v[96:97]
	v_or_b32_e32 v97, v104, v101
	v_mul_f32_e32 v104, v92, v98
	v_cvt_pk_bf16_f32 v108, v104, s0
	v_or_b32_e32 v104, v97, v152
	v_lshlrev_b64 v[106:107], 7, v[104:105]
	v_lshl_add_u64 v[106:107], v[102:103], 0, v[106:107]
	v_mul_f32_e32 v104, v93, v98
	global_store_short v[106:107], v108, off
	v_cvt_pk_bf16_f32 v108, v104, s0
	v_or_b32_e32 v104, v97, v151
	v_lshlrev_b64 v[106:107], 7, v[104:105]
	v_lshl_add_u64 v[106:107], v[102:103], 0, v[106:107]
	v_mul_f32_e32 v104, v94, v98
	global_store_short v[106:107], v108, off
	v_cvt_pk_bf16_f32 v108, v104, s0
	v_or_b32_e32 v104, v97, v150
	v_lshlrev_b64 v[106:107], 7, v[104:105]
	v_lshl_add_u64 v[106:107], v[102:103], 0, v[106:107]
	v_mul_f32_e32 v104, v95, v98
	global_store_short v[106:107], v108, off
	v_cvt_pk_bf16_f32 v106, v104, s0
	v_or_b32_e32 v104, v97, v149
	v_lshlrev_b64 v[104:105], 7, v[104:105]
	v_lshl_add_u64 v[104:105], v[102:103], 0, v[104:105]
	global_store_short v[104:105], v106, off
	v_add_u32_e32 v104, v157, v100
	v_ashrrev_i32_e32 v105, 31, v104
	v_lshlrev_b64 v[104:105], 12, v[104:105]
	v_or3_b32 v104, v104, v101, v156
	v_mul_f32_e32 v97, v88, v98
	v_lshlrev_b64 v[106:107], 7, v[104:105]
	v_cvt_pk_bf16_f32 v97, v97, s0
	v_lshl_add_u64 v[106:107], v[102:103], 0, v[106:107]
	global_store_short v[106:107], v97, off
	v_or_b32_e32 v106, 1, v104
	v_mov_b32_e32 v107, v105
	v_mul_f32_e32 v97, v89, v98
	v_lshlrev_b64 v[106:107], 7, v[106:107]
	v_cvt_pk_bf16_f32 v97, v97, s0
	v_lshl_add_u64 v[106:107], v[102:103], 0, v[106:107]
	global_store_short v[106:107], v97, off
	v_or_b32_e32 v106, 2, v104
	v_mov_b32_e32 v107, v105
	v_mul_f32_e32 v97, v90, v98
	v_lshlrev_b64 v[106:107], 7, v[106:107]
	v_cvt_pk_bf16_f32 v97, v97, s0
	v_lshl_add_u64 v[106:107], v[102:103], 0, v[106:107]
	v_or_b32_e32 v104, 3, v104
	global_store_short v[106:107], v97, off
	v_mul_f32_e32 v97, v91, v98
	v_lshlrev_b64 v[104:105], 7, v[104:105]
	v_cvt_pk_bf16_f32 v97, v97, s0
	v_lshl_add_u64 v[104:105], v[102:103], 0, v[104:105]
	global_store_short v[104:105], v97, off
	v_add_u32_e32 v104, v155, v100
	v_ashrrev_i32_e32 v105, 31, v104
	v_lshlrev_b64 v[104:105], 12, v[104:105]
	v_or_b32_e32 v97, v104, v101
	v_mul_f32_e32 v104, v84, v98
	v_cvt_pk_bf16_f32 v108, v104, s0
	v_or_b32_e32 v104, v97, v152
	v_lshlrev_b64 v[106:107], 7, v[104:105]
	v_lshl_add_u64 v[106:107], v[102:103], 0, v[106:107]
	v_mul_f32_e32 v104, v85, v98
	global_store_short v[106:107], v108, off
	v_cvt_pk_bf16_f32 v108, v104, s0
	v_or_b32_e32 v104, v97, v151
	v_lshlrev_b64 v[106:107], 7, v[104:105]
	v_lshl_add_u64 v[106:107], v[102:103], 0, v[106:107]
	v_mul_f32_e32 v104, v86, v98
	global_store_short v[106:107], v108, off
	v_cvt_pk_bf16_f32 v108, v104, s0
	v_or_b32_e32 v104, v97, v150
	v_lshlrev_b64 v[106:107], 7, v[104:105]
	v_lshl_add_u64 v[106:107], v[102:103], 0, v[106:107]
	v_mul_f32_e32 v104, v87, v98
	global_store_short v[106:107], v108, off
	v_cvt_pk_bf16_f32 v106, v104, s0
	v_or_b32_e32 v104, v97, v149
	v_lshlrev_b64 v[104:105], 7, v[104:105]
	v_lshl_add_u64 v[104:105], v[102:103], 0, v[104:105]
	global_store_short v[104:105], v106, off
	v_add_u32_e32 v104, v153, v100
	v_ashrrev_i32_e32 v105, 31, v104
	v_lshlrev_b64 v[104:105], 12, v[104:105]
	v_or3_b32 v104, v104, v101, v154
	v_mul_f32_e32 v97, v80, v98
	v_lshlrev_b64 v[106:107], 7, v[104:105]
	v_cvt_pk_bf16_f32 v97, v97, s0
	v_lshl_add_u64 v[106:107], v[102:103], 0, v[106:107]
	global_store_short v[106:107], v97, off
	v_or_b32_e32 v106, 1, v104
	v_mov_b32_e32 v107, v105
	v_mul_f32_e32 v97, v81, v98
	v_lshlrev_b64 v[106:107], 7, v[106:107]
	v_cvt_pk_bf16_f32 v97, v97, s0
	v_lshl_add_u64 v[106:107], v[102:103], 0, v[106:107]
	global_store_short v[106:107], v97, off
	v_or_b32_e32 v106, 2, v104
	v_mov_b32_e32 v107, v105
	v_mul_f32_e32 v97, v82, v98
	v_lshlrev_b64 v[106:107], 7, v[106:107]
	v_cvt_pk_bf16_f32 v97, v97, s0
	v_lshl_add_u64 v[106:107], v[102:103], 0, v[106:107]
	v_or_b32_e32 v104, 3, v104
	global_store_short v[106:107], v97, off
	v_mul_f32_e32 v97, v83, v98
	v_lshlrev_b64 v[104:105], 7, v[104:105]
	v_cvt_pk_bf16_f32 v97, v97, s0
	v_lshl_add_u64 v[102:103], v[102:103], 0, v[104:105]
	s_mov_b64 s[74:75], 0
	global_store_short v[102:103], v97, off

; __device__ __forceinline__ unsigned short bf1(float v) { return (unsigned short)(cvt_pk_bf16(v, 0.f) & 0xffffu); }
; __device__ __forceinline__ void st4(bf16_t* p, f32x4 v) { u32x2 w; w.x = cvt_pk_bf16(v[0], v[1]); w.y = cvt_pk_bf16(v[2], v[3]); *(u32x2*)p = w; }
;     __device__ __forceinline__ void operator()(const f32x4 (&acc)[2][2][4][2], const Unit& u, int wr, int wc, int fr, int fq) const {
;     ...
;             for (int m = 0; m < 4; ++m) { const int row = row0 + ai * HALF + m * 16; const f32x4 sq = *(const f32x4*)(SSQKV + row * 4);
;                 const float sc = 1.0f / sqrtf(((sq[0] + sq[1]) + (sq[2] + sq[3])) * (1.f / 128.f) + NEPS);
;                 if (u.pn < 2) {
; #pragma unroll
;                     for (int bj = 0; bj < 2; ++bj)
; #pragma unroll
;                         for (int n = 0; n < 2; ++n) { const int c = u.pn * BM + bj * HALF + wc * 32 + n * 16 + 4 * fq; st4(KN + ((((size_t)((row >> 12) * 8 + (c >> 6)) * 64 + ((row & (SEQL - 1)) >> 6)) * 64 + (row & 63)) * 64) + (c & 63), acc[ai][bj][m][n] * sc); }
;                 } else {
; #pragma unroll
;                     for (int bj = 0; bj < 2; ++bj)
; #pragma unroll
;                         for (int n = 0; n < 2; ++n)
; #pragma unroll
;                             for (int i = 0; i < 4; ++i) { const int c = (u.pn - 2) * BM + bj * HALF + wc * 32 + n * 16 + 4 * fq + i; VTM[((((size_t)((row >> 12) * 8 + (c >> 6)) * 64 + ((row & (SEQL - 1)) >> 6)) * 64 + (c & 63)) * 64) + (row & 63)] = bf1(acc[ai][bj][m][n][i] * sc); }
.LBB0_686:
	v_add_u32_e32 v83, 48, v161
	v_lshlrev_b32_e32 v80, 2, v83
	v_ashrrev_i32_e32 v81, 31, v80
	v_lshl_add_u64 v[80:81], v[80:81], 2, s[14:15]
	v_add_u32_e32 v80, 48, v166
	v_and_b32_e32 v80, 63, v80
	s_mov_b64 s[74:75], -1
	v_lshlrev_b32_e32 v80, 1, v80
	v_add_f32_e32 v81, v218, v219
	v_add_f32_e32 v82, v220, v221
	v_add_f32_e32 v81, v81, v82
	v_fmamk_f32 v81, v81, 0x3c000000, v147
	v_mul_f32_e32 v82, 0x4f800000, v81
	v_cmp_gt_f32_e32 vcc, s69, v81
	v_ashrrev_i32_e32 v84, 9, v83
	v_and_b32_e32 v84, -8, v84
	v_cndmask_b32_e32 v81, v81, v82, vcc
	v_sqrt_f32_e32 v82, v81
	s_nop 0
	v_add_u32_e32 v85, -1, v82
	v_add_u32_e32 v86, 1, v82
	v_fma_f32 v87, -v85, v82, v81
	v_fma_f32 v88, -v86, v82, v81
	v_cmp_ge_f32_e64 s[10:11], 0, v87
	s_nop 1
	v_cndmask_b32_e64 v82, v82, v85, s[10:11]
	v_cmp_lt_f32_e64 s[10:11], 0, v88
	s_nop 1
	v_cndmask_b32_e64 v82, v82, v86, s[10:11]
	v_mul_f32_e32 v85, 0x37800000, v82
	v_cndmask_b32_e32 v82, v82, v85, vcc
	v_cmp_class_f32_e32 vcc, v81, v148
	s_nop 1
	v_cndmask_b32_e32 v81, v82, v81, vcc
	v_div_scale_f32 v82, s[10:11], v81, v81, 1.0
	v_rcp_f32_e32 v85, v82
	v_div_scale_f32 v86, vcc, 1.0, v81, 1.0
	v_fma_f32 v87, -v82, v85, 1.0
	v_fmac_f32_e32 v85, v87, v85
	v_mul_f32_e32 v87, v86, v85
	v_fma_f32 v88, -v82, v87, v86
	v_fmac_f32_e32 v87, v88, v85
	v_fma_f32 v82, -v82, v87, v86
	v_div_fmas_f32 v82, v82, v85, v87
	s_and_b64 vcc, exec, s[6:7]
	v_div_fixup_f32 v82, v82, v81, 1.0
	s_cbranch_vccnz .LBB0_688
	v_add_u32_e32 v88, v84, v159
	v_ashrrev_i32_e32 v89, 31, v88
	v_and_b32_e32 v85, 0xfc0, v83
	v_mov_b32_e32 v81, v133
	v_lshlrev_b64 v[88:89], 12, v[88:89]
	v_lshl_add_u64 v[86:87], s[52:53], 0, v[80:81]
	v_or_b32_e32 v81, v88, v85
	v_mul_f32_e32 v88, v76, v82
	v_cvt_pk_bf16_f32 v92, v88, s0
	v_or_b32_e32 v88, v81, v152
	v_lshlrev_b64 v[90:91], 7, v[88:89]
	v_lshl_add_u64 v[90:91], v[86:87], 0, v[90:91]
	v_mul_f32_e32 v88, v77, v82
	global_store_short v[90:91], v92, off
	v_cvt_pk_bf16_f32 v92, v88, s0
	v_or_b32_e32 v88, v81, v151
	v_lshlrev_b64 v[90:91], 7, v[88:89]
	v_lshl_add_u64 v[90:91], v[86:87], 0, v[90:91]
	v_mul_f32_e32 v88, v78, v82
	global_store_short v[90:91], v92, off
	v_cvt_pk_bf16_f32 v92, v88, s0
	v_or_b32_e32 v88, v81, v150
	v_lshlrev_b64 v[90:91], 7, v[88:89]
	v_lshl_add_u64 v[90:91], v[86:87], 0, v[90:91]
	v_mul_f32_e32 v88, v79, v82
	global_store_short v[90:91], v92, off
	v_cvt_pk_bf16_f32 v90, v88, s0
	v_or_b32_e32 v88, v81, v149
	v_lshlrev_b64 v[88:89], 7, v[88:89]
	v_lshl_add_u64 v[88:89], v[86:87], 0, v[88:89]
	global_store_short v[88:89], v90, off
	v_add_u32_e32 v88, v157, v84
	v_ashrrev_i32_e32 v89, 31, v88
	v_lshlrev_b64 v[88:89], 12, v[88:89]
	v_or3_b32 v88, v88, v85, v156
	v_mul_f32_e32 v81, v72, v82
	v_lshlrev_b64 v[90:91], 7, v[88:89]
	v_cvt_pk_bf16_f32 v81, v81, s0
	v_lshl_add_u64 v[90:91], v[86:87], 0, v[90:91]
	global_store_short v[90:91], v81, off
	v_or_b32_e32 v90, 1, v88
	v_mov_b32_e32 v91, v89
	v_mul_f32_e32 v81, v73, v82
	v_lshlrev_b64 v[90:91], 7, v[90:91]
	v_cvt_pk_bf16_f32 v81, v81, s0
	v_lshl_add_u64 v[90:91], v[86:87], 0, v[90:91]
	global_store_short v[90:91], v81, off
	v_or_b32_e32 v90, 2, v88
	v_mov_b32_e32 v91, v89
	v_mul_f32_e32 v81, v74, v82
	v_lshlrev_b64 v[90:91], 7, v[90:91]
	v_cvt_pk_bf16_f32 v81, v81, s0
	v_lshl_add_u64 v[90:91], v[86:87], 0, v[90:91]
	v_or_b32_e32 v88, 3, v88
	global_store_short v[90:91], v81, off
	v_mul_f32_e32 v81, v75, v82
	v_lshlrev_b64 v[88:89], 7, v[88:89]
	v_cvt_pk_bf16_f32 v81, v81, s0
	v_lshl_add_u64 v[88:89], v[86:87], 0, v[88:89]
	global_store_short v[88:89], v81, off
	v_add_u32_e32 v88, v155, v84
	v_ashrrev_i32_e32 v89, 31, v88
	v_lshlrev_b64 v[88:89], 12, v[88:89]
	v_or_b32_e32 v81, v88, v85
	v_mul_f32_e32 v88, v68, v82
	v_cvt_pk_bf16_f32 v92, v88, s0
	v_or_b32_e32 v88, v81, v152
	v_lshlrev_b64 v[90:91], 7, v[88:89]
	v_lshl_add_u64 v[90:91], v[86:87], 0, v[90:91]
	v_mul_f32_e32 v88, v69, v82
	global_store_short v[90:91], v92, off
	v_cvt_pk_bf16_f32 v92, v88, s0
	v_or_b32_e32 v88, v81, v151
	v_lshlrev_b64 v[90:91], 7, v[88:89]
	v_lshl_add_u64 v[90:91], v[86:87], 0, v[90:91]
	v_mul_f32_e32 v88, v70, v82
	global_store_short v[90:91], v92, off
	v_cvt_pk_bf16_f32 v92, v88, s0
	v_or_b32_e32 v88, v81, v150
	v_lshlrev_b64 v[90:91], 7, v[88:89]
	v_lshl_add_u64 v[90:91], v[86:87], 0, v[90:91]
	v_mul_f32_e32 v88, v71, v82
	global_store_short v[90:91], v92, off
	v_cvt_pk_bf16_f32 v90, v88, s0
	v_or_b32_e32 v88, v81, v149
	v_lshlrev_b64 v[88:89], 7, v[88:89]
	v_lshl_add_u64 v[88:89], v[86:87], 0, v[88:89]
	global_store_short v[88:89], v90, off
	v_add_u32_e32 v88, v153, v84
	v_ashrrev_i32_e32 v89, 31, v88
	v_lshlrev_b64 v[88:89], 12, v[88:89]
	v_or3_b32 v88, v88, v85, v154
	v_mul_f32_e32 v81, v64, v82
	v_lshlrev_b64 v[90:91], 7, v[88:89]
	v_cvt_pk_bf16_f32 v81, v81, s0
	v_lshl_add_u64 v[90:91], v[86:87], 0, v[90:91]
	global_store_short v[90:91], v81, off
	v_or_b32_e32 v90, 1, v88
	v_mov_b32_e32 v91, v89
	v_mul_f32_e32 v81, v65, v82
	v_lshlrev_b64 v[90:91], 7, v[90:91]
	v_cvt_pk_bf16_f32 v81, v81, s0
	v_lshl_add_u64 v[90:91], v[86:87], 0, v[90:91]
	global_store_short v[90:91], v81, off
	v_or_b32_e32 v90, 2, v88
	v_mov_b32_e32 v91, v89
	v_mul_f32_e32 v81, v66, v82
	v_lshlrev_b64 v[90:91], 7, v[90:91]
	v_cvt_pk_bf16_f32 v81, v81, s0
	v_lshl_add_u64 v[90:91], v[86:87], 0, v[90:91]
	v_or_b32_e32 v88, 3, v88
	global_store_short v[90:91], v81, off
	v_mul_f32_e32 v81, v67, v82
	v_lshlrev_b64 v[88:89], 7, v[88:89]
	v_cvt_pk_bf16_f32 v81, v81, s0
	v_lshl_add_u64 v[86:87], v[86:87], 0, v[88:89]
	s_mov_b64 s[74:75], 0
	global_store_short v[86:87], v81, off

; __device__ __forceinline__ unsigned short bf1(float v) { return (unsigned short)(cvt_pk_bf16(v, 0.f) & 0xffffu); }
; __device__ __forceinline__ void st4(bf16_t* p, f32x4 v) { u32x2 w; w.x = cvt_pk_bf16(v[0], v[1]); w.y = cvt_pk_bf16(v[2], v[3]); *(u32x2*)p = w; }
;     __device__ __forceinline__ void operator()(const f32x4 (&acc)[2][2][4][2], const Unit& u, int wr, int wc, int fr, int fq) const {
;     ...
;             for (int m = 0; m < 4; ++m) { const int row = row0 + ai * HALF + m * 16; const f32x4 sq = *(const f32x4*)(SSQKV + row * 4);
;                 const float sc = 1.0f / sqrtf(((sq[0] + sq[1]) + (sq[2] + sq[3])) * (1.f / 128.f) + NEPS);
;                 if (u.pn < 2) {
; #pragma unroll
;                     for (int bj = 0; bj < 2; ++bj)
; #pragma unroll
;                         for (int n = 0; n < 2; ++n) { const int c = u.pn * BM + bj * HALF + wc * 32 + n * 16 + 4 * fq; st4(KN + ((((size_t)((row >> 12) * 8 + (c >> 6)) * 64 + ((row & (SEQL - 1)) >> 6)) * 64 + (row & 63)) * 64) + (c & 63), acc[ai][bj][m][n] * sc); }
;                 } else {
; #pragma unroll
;                     for (int bj = 0; bj < 2; ++bj)
; #pragma unroll
;                         for (int n = 0; n < 2; ++n)
; #pragma unroll
;                             for (int i = 0; i < 4; ++i) { const int c = (u.pn - 2) * BM + bj * HALF + wc * 32 + n * 16 + 4 * fq + i; VTM[((((size_t)((row >> 12) * 8 + (c >> 6)) * 64 + ((row & (SEQL - 1)) >> 6)) * 64 + (c & 63)) * 64) + (row & 63)] = bf1(acc[ai][bj][m][n][i] * sc); }
.LBB0_690:
	v_add_u32_e32 v65, 0x80, v161
	v_lshlrev_b32_e32 v66, 2, v65
	v_ashrrev_i32_e32 v67, 31, v66
	v_lshl_add_u64 v[66:67], v[66:67], 2, s[14:15]
	v_add_f32_e32 v64, v222, v223
	v_add_f32_e32 v66, v224, v225
	v_add_f32_e32 v64, v64, v66
	v_fmamk_f32 v64, v64, 0x3c000000, v147
	v_mul_f32_e32 v66, 0x4f800000, v64
	v_cmp_gt_f32_e32 vcc, s69, v64
	v_ashrrev_i32_e32 v67, 9, v65
	s_nop 0
	v_cndmask_b32_e32 v64, v64, v66, vcc
	v_sqrt_f32_e32 v66, v64
	s_nop 0
	v_add_u32_e32 v68, -1, v66
	v_add_u32_e32 v69, 1, v66
	v_fma_f32 v70, -v68, v66, v64
	v_fma_f32 v71, -v69, v66, v64
	v_cmp_ge_f32_e64 s[10:11], 0, v70
	s_nop 1
	v_cndmask_b32_e64 v66, v66, v68, s[10:11]
	v_cmp_lt_f32_e64 s[10:11], 0, v71
	s_nop 1
	v_cndmask_b32_e64 v66, v66, v69, s[10:11]
	v_mul_f32_e32 v68, 0x37800000, v66
	v_cndmask_b32_e32 v66, v66, v68, vcc
	v_cmp_class_f32_e32 vcc, v64, v148
	s_nop 1
	v_cndmask_b32_e32 v64, v66, v64, vcc
	v_div_scale_f32 v68, s[10:11], v64, v64, 1.0
	v_rcp_f32_e32 v69, v68
	v_and_b32_e32 v66, -8, v67
	v_div_scale_f32 v67, vcc, 1.0, v64, 1.0
	v_fma_f32 v70, -v68, v69, 1.0
	v_fmac_f32_e32 v69, v70, v69
	v_mul_f32_e32 v70, v67, v69
	v_fma_f32 v71, -v68, v70, v67
	v_fmac_f32_e32 v70, v71, v69
	v_fma_f32 v67, -v68, v70, v67
	v_div_fmas_f32 v67, v67, v69, v70
	s_and_b64 vcc, exec, s[6:7]
	v_div_fixup_f32 v64, v67, v64, 1.0
	s_mov_b64 s[10:11], -1
	s_cbranch_vccnz .LBB0_692
	v_add_u32_e32 v70, v66, v159
	v_ashrrev_i32_e32 v71, 31, v70
	v_and_b32_e32 v67, 0xfc0, v65
	v_lshlrev_b64 v[70:71], 12, v[70:71]
	v_or_b32_e32 v74, v70, v67
	v_mul_f32_e32 v70, v60, v64
	v_cvt_pk_bf16_f32 v75, v70, s0
	v_or_b32_e32 v70, v74, v152
	v_lshl_add_u64 v[68:69], s[52:53], 0, v[132:133]
	v_lshlrev_b64 v[72:73], 7, v[70:71]
	v_lshl_add_u64 v[72:73], v[68:69], 0, v[72:73]
	v_mul_f32_e32 v70, v61, v64
	global_store_short v[72:73], v75, off
	v_cvt_pk_bf16_f32 v75, v70, s0
	v_or_b32_e32 v70, v74, v151
	v_lshlrev_b64 v[72:73], 7, v[70:71]
	v_lshl_add_u64 v[72:73], v[68:69], 0, v[72:73]
	v_mul_f32_e32 v70, v62, v64
	global_store_short v[72:73], v75, off
	v_cvt_pk_bf16_f32 v75, v70, s0
	v_or_b32_e32 v70, v74, v150
	v_lshlrev_b64 v[72:73], 7, v[70:71]
	v_lshl_add_u64 v[72:73], v[68:69], 0, v[72:73]
	v_mul_f32_e32 v70, v63, v64
	global_store_short v[72:73], v75, off
	v_cvt_pk_bf16_f32 v72, v70, s0
	v_or_b32_e32 v70, v74, v149
	v_lshlrev_b64 v[70:71], 7, v[70:71]
	v_lshl_add_u64 v[70:71], v[68:69], 0, v[70:71]
	global_store_short v[70:71], v72, off
	v_add_u32_e32 v70, v157, v66
	v_ashrrev_i32_e32 v71, 31, v70
	v_lshlrev_b64 v[70:71], 12, v[70:71]
	v_mul_f32_e32 v72, v56, v64
	v_or3_b32 v70, v70, v67, v156
	v_cvt_pk_bf16_f32 v74, v72, s0
	v_lshlrev_b64 v[72:73], 7, v[70:71]
	v_lshl_add_u64 v[72:73], v[68:69], 0, v[72:73]
	global_store_short v[72:73], v74, off
	v_mul_f32_e32 v72, v57, v64
	v_cvt_pk_bf16_f32 v74, v72, s0
	v_or_b32_e32 v72, 1, v70
	v_mov_b32_e32 v73, v71
	v_lshlrev_b64 v[72:73], 7, v[72:73]
	v_lshl_add_u64 v[72:73], v[68:69], 0, v[72:73]
	global_store_short v[72:73], v74, off
	v_mul_f32_e32 v72, v58, v64
	v_cvt_pk_bf16_f32 v74, v72, s0
	v_or_b32_e32 v72, 2, v70
	v_mov_b32_e32 v73, v71
	v_lshlrev_b64 v[72:73], 7, v[72:73]
	v_lshl_add_u64 v[72:73], v[68:69], 0, v[72:73]
	v_or_b32_e32 v70, 3, v70
	global_store_short v[72:73], v74, off
	v_mul_f32_e32 v72, v59, v64
	v_lshlrev_b64 v[70:71], 7, v[70:71]
	v_cvt_pk_bf16_f32 v72, v72, s0
	v_lshl_add_u64 v[70:71], v[68:69], 0, v[70:71]
	global_store_short v[70:71], v72, off
	v_add_u32_e32 v70, v155, v66
	v_ashrrev_i32_e32 v71, 31, v70
	v_lshlrev_b64 v[70:71], 12, v[70:71]
	v_or_b32_e32 v74, v70, v67
	v_mul_f32_e32 v70, v52, v64
	v_cvt_pk_bf16_f32 v75, v70, s0
	v_or_b32_e32 v70, v74, v152
	v_lshlrev_b64 v[72:73], 7, v[70:71]
	v_lshl_add_u64 v[72:73], v[68:69], 0, v[72:73]
	v_mul_f32_e32 v70, v53, v64
	global_store_short v[72:73], v75, off
	v_cvt_pk_bf16_f32 v75, v70, s0
	v_or_b32_e32 v70, v74, v151
	v_lshlrev_b64 v[72:73], 7, v[70:71]
	v_lshl_add_u64 v[72:73], v[68:69], 0, v[72:73]
	v_mul_f32_e32 v70, v54, v64
	global_store_short v[72:73], v75, off
	v_cvt_pk_bf16_f32 v75, v70, s0
	v_or_b32_e32 v70, v74, v150
	v_lshlrev_b64 v[72:73], 7, v[70:71]
	v_lshl_add_u64 v[72:73], v[68:69], 0, v[72:73]
	v_mul_f32_e32 v70, v55, v64
	global_store_short v[72:73], v75, off
	v_cvt_pk_bf16_f32 v72, v70, s0
	v_or_b32_e32 v70, v74, v149
	v_lshlrev_b64 v[70:71], 7, v[70:71]
	v_lshl_add_u64 v[70:71], v[68:69], 0, v[70:71]
	global_store_short v[70:71], v72, off
	v_add_u32_e32 v70, v153, v66
	v_ashrrev_i32_e32 v71, 31, v70
	v_lshlrev_b64 v[70:71], 12, v[70:71]
	v_mul_f32_e32 v72, v48, v64
	v_or3_b32 v70, v70, v67, v154
	v_cvt_pk_bf16_f32 v74, v72, s0
	v_lshlrev_b64 v[72:73], 7, v[70:71]
	v_lshl_add_u64 v[72:73], v[68:69], 0, v[72:73]
	global_store_short v[72:73], v74, off
	v_or_b32_e32 v72, 1, v70
	v_mov_b32_e32 v73, v71
	v_mul_f32_e32 v67, v49, v64
	v_lshlrev_b64 v[72:73], 7, v[72:73]
	v_cvt_pk_bf16_f32 v67, v67, s0
	v_lshl_add_u64 v[72:73], v[68:69], 0, v[72:73]
	global_store_short v[72:73], v67, off
	v_or_b32_e32 v72, 2, v70
	v_mov_b32_e32 v73, v71
	v_mul_f32_e32 v67, v50, v64
	v_lshlrev_b64 v[72:73], 7, v[72:73]
	v_cvt_pk_bf16_f32 v67, v67, s0
	v_lshl_add_u64 v[72:73], v[68:69], 0, v[72:73]
	v_or_b32_e32 v70, 3, v70
	global_store_short v[72:73], v67, off
	v_mul_f32_e32 v67, v51, v64
	v_lshlrev_b64 v[70:71], 7, v[70:71]
	v_cvt_pk_bf16_f32 v67, v67, s0
	v_lshl_add_u64 v[68:69], v[68:69], 0, v[70:71]
	s_mov_b64 s[10:11], 0
	global_store_short v[68:69], v67, off

; __device__ __forceinline__ unsigned short bf1(float v) { return (unsigned short)(cvt_pk_bf16(v, 0.f) & 0xffffu); }
; __device__ __forceinline__ void st4(bf16_t* p, f32x4 v) { u32x2 w; w.x = cvt_pk_bf16(v[0], v[1]); w.y = cvt_pk_bf16(v[2], v[3]); *(u32x2*)p = w; }
;     __device__ __forceinline__ void operator()(const f32x4 (&acc)[2][2][4][2], const Unit& u, int wr, int wc, int fr, int fq) const {
;     ...
;             for (int m = 0; m < 4; ++m) { const int row = row0 + ai * HALF + m * 16; const f32x4 sq = *(const f32x4*)(SSQKV + row * 4);
;                 const float sc = 1.0f / sqrtf(((sq[0] + sq[1]) + (sq[2] + sq[3])) * (1.f / 128.f) + NEPS);
;                 if (u.pn < 2) {
; #pragma unroll
;                     for (int bj = 0; bj < 2; ++bj)
; #pragma unroll
;                         for (int n = 0; n < 2; ++n) { const int c = u.pn * BM + bj * HALF + wc * 32 + n * 16 + 4 * fq; st4(KN + ((((size_t)((row >> 12) * 8 + (c >> 6)) * 64 + ((row & (SEQL - 1)) >> 6)) * 64 + (row & 63)) * 64) + (c & 63), acc[ai][bj][m][n] * sc); }
;                 } else {
; #pragma unroll
;                     for (int bj = 0; bj < 2; ++bj)
; #pragma unroll
;                         for (int n = 0; n < 2; ++n)
; #pragma unroll
;                             for (int i = 0; i < 4; ++i) { const int c = (u.pn - 2) * BM + bj * HALF + wc * 32 + n * 16 + 4 * fq + i; VTM[((((size_t)((row >> 12) * 8 + (c >> 6)) * 64 + ((row & (SEQL - 1)) >> 6)) * 64 + (c & 63)) * 64) + (row & 63)] = bf1(acc[ai][bj][m][n][i] * sc); }
.LBB0_694:
	v_add_u32_e32 v49, 0x90, v161
	v_lshlrev_b32_e32 v50, 2, v49
	v_ashrrev_i32_e32 v51, 31, v50
	v_lshl_add_u64 v[50:51], v[50:51], 2, s[14:15]
	v_add_f32_e32 v48, v226, v227
	v_add_f32_e32 v50, v228, v229
	v_add_f32_e32 v48, v48, v50
	v_fmamk_f32 v48, v48, 0x3c000000, v147
	v_mul_f32_e32 v50, 0x4f800000, v48
	v_cmp_gt_f32_e32 vcc, s69, v48
	v_ashrrev_i32_e32 v51, 9, v49
	s_nop 0
	v_cndmask_b32_e32 v48, v48, v50, vcc
	v_sqrt_f32_e32 v50, v48
	s_nop 0
	v_add_u32_e32 v52, -1, v50
	v_add_u32_e32 v53, 1, v50
	v_fma_f32 v54, -v52, v50, v48
	v_fma_f32 v55, -v53, v50, v48
	v_cmp_ge_f32_e64 s[10:11], 0, v54
	s_nop 1
	v_cndmask_b32_e64 v50, v50, v52, s[10:11]
	v_cmp_lt_f32_e64 s[10:11], 0, v55
	s_nop 1
	v_cndmask_b32_e64 v50, v50, v53, s[10:11]
	v_mul_f32_e32 v52, 0x37800000, v50
	v_cndmask_b32_e32 v50, v50, v52, vcc
	v_cmp_class_f32_e32 vcc, v48, v148
	s_nop 1
	v_cndmask_b32_e32 v48, v50, v48, vcc
	v_div_scale_f32 v52, s[10:11], v48, v48, 1.0
	v_rcp_f32_e32 v53, v52
	v_and_b32_e32 v50, -8, v51
	v_div_scale_f32 v51, vcc, 1.0, v48, 1.0
	v_fma_f32 v54, -v52, v53, 1.0
	v_fmac_f32_e32 v53, v54, v53
	v_mul_f32_e32 v54, v51, v53
	v_fma_f32 v55, -v52, v54, v51
	v_fmac_f32_e32 v54, v55, v53
	v_fma_f32 v51, -v52, v54, v51
	v_div_fmas_f32 v51, v51, v53, v54
	s_and_b64 vcc, exec, s[6:7]
	v_div_fixup_f32 v48, v51, v48, 1.0
	s_mov_b64 s[10:11], -1
	s_cbranch_vccnz .LBB0_696
	v_add_u32_e32 v54, v50, v159
	v_ashrrev_i32_e32 v55, 31, v54
	v_and_b32_e32 v51, 0xfc0, v49
	v_lshlrev_b64 v[54:55], 12, v[54:55]
	v_or_b32_e32 v58, v54, v51
	v_mul_f32_e32 v54, v44, v48
	v_mov_b32_e32 v113, v133
	v_cvt_pk_bf16_f32 v59, v54, s0
	v_or_b32_e32 v54, v58, v152
	v_lshl_add_u64 v[52:53], s[52:53], 0, v[112:113]
	v_lshlrev_b64 v[56:57], 7, v[54:55]
	v_lshl_add_u64 v[56:57], v[52:53], 0, v[56:57]
	v_mul_f32_e32 v54, v45, v48
	global_store_short v[56:57], v59, off
	v_cvt_pk_bf16_f32 v59, v54, s0
	v_or_b32_e32 v54, v58, v151
	v_lshlrev_b64 v[56:57], 7, v[54:55]
	v_lshl_add_u64 v[56:57], v[52:53], 0, v[56:57]
	v_mul_f32_e32 v54, v46, v48
	global_store_short v[56:57], v59, off
	v_cvt_pk_bf16_f32 v59, v54, s0
	v_or_b32_e32 v54, v58, v150
	v_lshlrev_b64 v[56:57], 7, v[54:55]
	v_lshl_add_u64 v[56:57], v[52:53], 0, v[56:57]
	v_mul_f32_e32 v54, v47, v48
	global_store_short v[56:57], v59, off
	v_cvt_pk_bf16_f32 v56, v54, s0
	v_or_b32_e32 v54, v58, v149
	v_lshlrev_b64 v[54:55], 7, v[54:55]
	v_lshl_add_u64 v[54:55], v[52:53], 0, v[54:55]
	global_store_short v[54:55], v56, off
	v_add_u32_e32 v54, v157, v50
	v_ashrrev_i32_e32 v55, 31, v54
	v_lshlrev_b64 v[54:55], 12, v[54:55]
	v_mul_f32_e32 v56, v40, v48
	v_or3_b32 v54, v54, v51, v156
	v_cvt_pk_bf16_f32 v58, v56, s0
	v_lshlrev_b64 v[56:57], 7, v[54:55]
	v_lshl_add_u64 v[56:57], v[52:53], 0, v[56:57]
	global_store_short v[56:57], v58, off
	v_mul_f32_e32 v56, v41, v48
	v_cvt_pk_bf16_f32 v58, v56, s0
	v_or_b32_e32 v56, 1, v54
	v_mov_b32_e32 v57, v55
	v_lshlrev_b64 v[56:57], 7, v[56:57]
	v_lshl_add_u64 v[56:57], v[52:53], 0, v[56:57]
	global_store_short v[56:57], v58, off
	v_mul_f32_e32 v56, v42, v48
	v_cvt_pk_bf16_f32 v58, v56, s0
	v_or_b32_e32 v56, 2, v54
	v_mov_b32_e32 v57, v55
	v_lshlrev_b64 v[56:57], 7, v[56:57]
	v_lshl_add_u64 v[56:57], v[52:53], 0, v[56:57]
	v_or_b32_e32 v54, 3, v54
	global_store_short v[56:57], v58, off
	v_mul_f32_e32 v56, v43, v48
	v_lshlrev_b64 v[54:55], 7, v[54:55]
	v_cvt_pk_bf16_f32 v56, v56, s0
	v_lshl_add_u64 v[54:55], v[52:53], 0, v[54:55]
	global_store_short v[54:55], v56, off
	v_add_u32_e32 v54, v155, v50
	v_ashrrev_i32_e32 v55, 31, v54
	v_lshlrev_b64 v[54:55], 12, v[54:55]
	v_or_b32_e32 v58, v54, v51
	v_mul_f32_e32 v54, v36, v48
	v_cvt_pk_bf16_f32 v59, v54, s0
	v_or_b32_e32 v54, v58, v152
	v_lshlrev_b64 v[56:57], 7, v[54:55]
	v_lshl_add_u64 v[56:57], v[52:53], 0, v[56:57]
	v_mul_f32_e32 v54, v37, v48
	global_store_short v[56:57], v59, off
	v_cvt_pk_bf16_f32 v59, v54, s0
	v_or_b32_e32 v54, v58, v151
	v_lshlrev_b64 v[56:57], 7, v[54:55]
	v_lshl_add_u64 v[56:57], v[52:53], 0, v[56:57]
	v_mul_f32_e32 v54, v38, v48
	global_store_short v[56:57], v59, off
	v_cvt_pk_bf16_f32 v59, v54, s0
	v_or_b32_e32 v54, v58, v150
	v_lshlrev_b64 v[56:57], 7, v[54:55]
	v_lshl_add_u64 v[56:57], v[52:53], 0, v[56:57]
	v_mul_f32_e32 v54, v39, v48
	global_store_short v[56:57], v59, off
	v_cvt_pk_bf16_f32 v56, v54, s0
	v_or_b32_e32 v54, v58, v149
	v_lshlrev_b64 v[54:55], 7, v[54:55]
	v_lshl_add_u64 v[54:55], v[52:53], 0, v[54:55]
	global_store_short v[54:55], v56, off
	v_add_u32_e32 v54, v153, v50
	v_ashrrev_i32_e32 v55, 31, v54
	v_lshlrev_b64 v[54:55], 12, v[54:55]
	v_mul_f32_e32 v56, v32, v48
	v_or3_b32 v54, v54, v51, v154
	v_cvt_pk_bf16_f32 v58, v56, s0
	v_lshlrev_b64 v[56:57], 7, v[54:55]
	v_lshl_add_u64 v[56:57], v[52:53], 0, v[56:57]
	global_store_short v[56:57], v58, off
	v_or_b32_e32 v56, 1, v54
	v_mov_b32_e32 v57, v55
	v_mul_f32_e32 v51, v33, v48
	v_lshlrev_b64 v[56:57], 7, v[56:57]
	v_cvt_pk_bf16_f32 v51, v51, s0
	v_lshl_add_u64 v[56:57], v[52:53], 0, v[56:57]
	global_store_short v[56:57], v51, off
	v_or_b32_e32 v56, 2, v54
	v_mov_b32_e32 v57, v55
	v_mul_f32_e32 v51, v34, v48
	v_lshlrev_b64 v[56:57], 7, v[56:57]
	v_cvt_pk_bf16_f32 v51, v51, s0
	v_lshl_add_u64 v[56:57], v[52:53], 0, v[56:57]
	v_or_b32_e32 v54, 3, v54
	global_store_short v[56:57], v51, off
	v_mul_f32_e32 v51, v35, v48
	v_lshlrev_b64 v[54:55], 7, v[54:55]
	v_cvt_pk_bf16_f32 v51, v51, s0
	v_lshl_add_u64 v[52:53], v[52:53], 0, v[54:55]
	s_mov_b64 s[10:11], 0
	global_store_short v[52:53], v51, off

; __device__ __forceinline__ unsigned short bf1(float v) { return (unsigned short)(cvt_pk_bf16(v, 0.f) & 0xffffu); }
; __device__ __forceinline__ void st4(bf16_t* p, f32x4 v) { u32x2 w; w.x = cvt_pk_bf16(v[0], v[1]); w.y = cvt_pk_bf16(v[2], v[3]); *(u32x2*)p = w; }
;     __device__ __forceinline__ void operator()(const f32x4 (&acc)[2][2][4][2], const Unit& u, int wr, int wc, int fr, int fq) const {
;     ...
;             for (int m = 0; m < 4; ++m) { const int row = row0 + ai * HALF + m * 16; const f32x4 sq = *(const f32x4*)(SSQKV + row * 4);
;                 const float sc = 1.0f / sqrtf(((sq[0] + sq[1]) + (sq[2] + sq[3])) * (1.f / 128.f) + NEPS);
;                 if (u.pn < 2) {
; #pragma unroll
;                     for (int bj = 0; bj < 2; ++bj)
; #pragma unroll
;                         for (int n = 0; n < 2; ++n) { const int c = u.pn * BM + bj * HALF + wc * 32 + n * 16 + 4 * fq; st4(KN + ((((size_t)((row >> 12) * 8 + (c >> 6)) * 64 + ((row & (SEQL - 1)) >> 6)) * 64 + (row & 63)) * 64) + (c & 63), acc[ai][bj][m][n] * sc); }
;                 } else {
; #pragma unroll
;                     for (int bj = 0; bj < 2; ++bj)
; #pragma unroll
;                         for (int n = 0; n < 2; ++n)
; #pragma unroll
;                             for (int i = 0; i < 4; ++i) { const int c = (u.pn - 2) * BM + bj * HALF + wc * 32 + n * 16 + 4 * fq + i; VTM[((((size_t)((row >> 12) * 8 + (c >> 6)) * 64 + ((row & (SEQL - 1)) >> 6)) * 64 + (c & 63)) * 64) + (row & 63)] = bf1(acc[ai][bj][m][n][i] * sc); }
.LBB0_698:
	v_add_u32_e32 v33, 0xa0, v161
	v_lshlrev_b32_e32 v34, 2, v33
	v_ashrrev_i32_e32 v35, 31, v34
	v_lshl_add_u64 v[34:35], v[34:35], 2, s[14:15]
	v_add_f32_e32 v32, v230, v231
	v_add_f32_e32 v34, v232, v233
	v_add_f32_e32 v32, v32, v34
	v_fmamk_f32 v32, v32, 0x3c000000, v147
	v_mul_f32_e32 v34, 0x4f800000, v32
	v_cmp_gt_f32_e32 vcc, s69, v32
	v_ashrrev_i32_e32 v35, 9, v33
	s_nop 0
	v_cndmask_b32_e32 v32, v32, v34, vcc
	v_sqrt_f32_e32 v34, v32
	s_nop 0
	v_add_u32_e32 v36, -1, v34
	v_add_u32_e32 v37, 1, v34
	v_fma_f32 v38, -v36, v34, v32
	v_fma_f32 v39, -v37, v34, v32
	v_cmp_ge_f32_e64 s[10:11], 0, v38
	s_nop 1
	v_cndmask_b32_e64 v34, v34, v36, s[10:11]
	v_cmp_lt_f32_e64 s[10:11], 0, v39
	s_nop 1
	v_cndmask_b32_e64 v34, v34, v37, s[10:11]
	v_mul_f32_e32 v36, 0x37800000, v34
	v_cndmask_b32_e32 v34, v34, v36, vcc
	v_cmp_class_f32_e32 vcc, v32, v148
	s_nop 1
	v_cndmask_b32_e32 v32, v34, v32, vcc
	v_div_scale_f32 v36, s[10:11], v32, v32, 1.0
	v_rcp_f32_e32 v37, v36
	v_and_b32_e32 v34, -8, v35
	v_div_scale_f32 v35, vcc, 1.0, v32, 1.0
	v_fma_f32 v38, -v36, v37, 1.0
	v_fmac_f32_e32 v37, v38, v37
	v_mul_f32_e32 v38, v35, v37
	v_fma_f32 v39, -v36, v38, v35
	v_fmac_f32_e32 v38, v39, v37
	v_fma_f32 v35, -v36, v38, v35
	v_div_fmas_f32 v35, v35, v37, v38
	s_and_b64 vcc, exec, s[6:7]
	v_div_fixup_f32 v32, v35, v32, 1.0
	s_mov_b64 s[10:11], -1
	s_cbranch_vccnz .LBB0_700
	v_add_u32_e32 v38, v34, v159
	v_ashrrev_i32_e32 v39, 31, v38
	v_and_b32_e32 v35, 0xfc0, v33
	v_lshlrev_b64 v[38:39], 12, v[38:39]
	v_or_b32_e32 v42, v38, v35
	v_mul_f32_e32 v38, v28, v32
	v_mov_b32_e32 v97, v133
	v_cvt_pk_bf16_f32 v43, v38, s0
	v_or_b32_e32 v38, v42, v152
	v_lshl_add_u64 v[36:37], s[52:53], 0, v[96:97]
	v_lshlrev_b64 v[40:41], 7, v[38:39]
	v_lshl_add_u64 v[40:41], v[36:37], 0, v[40:41]
	v_mul_f32_e32 v38, v29, v32
	global_store_short v[40:41], v43, off
	v_cvt_pk_bf16_f32 v43, v38, s0
	v_or_b32_e32 v38, v42, v151
	v_lshlrev_b64 v[40:41], 7, v[38:39]
	v_lshl_add_u64 v[40:41], v[36:37], 0, v[40:41]
	v_mul_f32_e32 v38, v30, v32
	global_store_short v[40:41], v43, off
	v_cvt_pk_bf16_f32 v43, v38, s0
	v_or_b32_e32 v38, v42, v150
	v_lshlrev_b64 v[40:41], 7, v[38:39]
	v_lshl_add_u64 v[40:41], v[36:37], 0, v[40:41]
	v_mul_f32_e32 v38, v31, v32
	global_store_short v[40:41], v43, off
	v_cvt_pk_bf16_f32 v40, v38, s0
	v_or_b32_e32 v38, v42, v149
	v_lshlrev_b64 v[38:39], 7, v[38:39]
	v_lshl_add_u64 v[38:39], v[36:37], 0, v[38:39]
	global_store_short v[38:39], v40, off
	v_add_u32_e32 v38, v157, v34
	v_ashrrev_i32_e32 v39, 31, v38
	v_lshlrev_b64 v[38:39], 12, v[38:39]
	v_mul_f32_e32 v40, v24, v32
	v_or3_b32 v38, v38, v35, v156
	v_cvt_pk_bf16_f32 v42, v40, s0
	v_lshlrev_b64 v[40:41], 7, v[38:39]
	v_lshl_add_u64 v[40:41], v[36:37], 0, v[40:41]
	global_store_short v[40:41], v42, off
	v_mul_f32_e32 v40, v25, v32
	v_cvt_pk_bf16_f32 v42, v40, s0
	v_or_b32_e32 v40, 1, v38
	v_mov_b32_e32 v41, v39
	v_lshlrev_b64 v[40:41], 7, v[40:41]
	v_lshl_add_u64 v[40:41], v[36:37], 0, v[40:41]
	global_store_short v[40:41], v42, off
	v_mul_f32_e32 v40, v26, v32
	v_cvt_pk_bf16_f32 v42, v40, s0
	v_or_b32_e32 v40, 2, v38
	v_mov_b32_e32 v41, v39
	v_lshlrev_b64 v[40:41], 7, v[40:41]
	v_lshl_add_u64 v[40:41], v[36:37], 0, v[40:41]
	v_or_b32_e32 v38, 3, v38
	global_store_short v[40:41], v42, off
	v_mul_f32_e32 v40, v27, v32
	v_lshlrev_b64 v[38:39], 7, v[38:39]
	v_cvt_pk_bf16_f32 v40, v40, s0
	v_lshl_add_u64 v[38:39], v[36:37], 0, v[38:39]
	global_store_short v[38:39], v40, off
	v_add_u32_e32 v38, v155, v34
	v_ashrrev_i32_e32 v39, 31, v38
	v_lshlrev_b64 v[38:39], 12, v[38:39]
	v_or_b32_e32 v42, v38, v35
	v_mul_f32_e32 v38, v20, v32
	v_cvt_pk_bf16_f32 v43, v38, s0
	v_or_b32_e32 v38, v42, v152
	v_lshlrev_b64 v[40:41], 7, v[38:39]
	v_lshl_add_u64 v[40:41], v[36:37], 0, v[40:41]
	v_mul_f32_e32 v38, v21, v32
	global_store_short v[40:41], v43, off
	v_cvt_pk_bf16_f32 v43, v38, s0
	v_or_b32_e32 v38, v42, v151
	v_lshlrev_b64 v[40:41], 7, v[38:39]
	v_lshl_add_u64 v[40:41], v[36:37], 0, v[40:41]
	v_mul_f32_e32 v38, v22, v32
	global_store_short v[40:41], v43, off
	v_cvt_pk_bf16_f32 v43, v38, s0
	v_or_b32_e32 v38, v42, v150
	v_lshlrev_b64 v[40:41], 7, v[38:39]
	v_lshl_add_u64 v[40:41], v[36:37], 0, v[40:41]
	v_mul_f32_e32 v38, v23, v32
	global_store_short v[40:41], v43, off
	v_cvt_pk_bf16_f32 v40, v38, s0
	v_or_b32_e32 v38, v42, v149
	v_lshlrev_b64 v[38:39], 7, v[38:39]
	v_lshl_add_u64 v[38:39], v[36:37], 0, v[38:39]
	global_store_short v[38:39], v40, off
	v_add_u32_e32 v38, v153, v34
	v_ashrrev_i32_e32 v39, 31, v38
	v_lshlrev_b64 v[38:39], 12, v[38:39]
	v_mul_f32_e32 v40, v16, v32
	v_or3_b32 v38, v38, v35, v154
	v_cvt_pk_bf16_f32 v42, v40, s0
	v_lshlrev_b64 v[40:41], 7, v[38:39]
	v_lshl_add_u64 v[40:41], v[36:37], 0, v[40:41]
	global_store_short v[40:41], v42, off
	v_or_b32_e32 v40, 1, v38
	v_mov_b32_e32 v41, v39
	v_mul_f32_e32 v35, v17, v32
	v_lshlrev_b64 v[40:41], 7, v[40:41]
	v_cvt_pk_bf16_f32 v35, v35, s0
	v_lshl_add_u64 v[40:41], v[36:37], 0, v[40:41]
	global_store_short v[40:41], v35, off
	v_or_b32_e32 v40, 2, v38
	v_mov_b32_e32 v41, v39
	v_mul_f32_e32 v35, v18, v32
	v_lshlrev_b64 v[40:41], 7, v[40:41]
	v_cvt_pk_bf16_f32 v35, v35, s0
	v_lshl_add_u64 v[40:41], v[36:37], 0, v[40:41]
	v_or_b32_e32 v38, 3, v38
	global_store_short v[40:41], v35, off
	v_mul_f32_e32 v35, v19, v32
	v_lshlrev_b64 v[38:39], 7, v[38:39]
	v_cvt_pk_bf16_f32 v35, v35, s0
	v_lshl_add_u64 v[36:37], v[36:37], 0, v[38:39]
	s_mov_b64 s[10:11], 0
	global_store_short v[36:37], v35, off

;     __device__ __forceinline__ void operator()(const f32x4 (&acc)[2][2][4][2], const Unit& u, int wr, int wc, int fr, int fq) const {
;     ...
;             for (int m = 0; m < 4; ++m) { const int row = row0 + ai * HALF + m * 16; const f32x4 sq = *(const f32x4*)(SSQKV + row * 4);
;                 const float sc = 1.0f / sqrtf(((sq[0] + sq[1]) + (sq[2] + sq[3])) * (1.f / 128.f) + NEPS);
;                 if (u.pn < 2) {
.LBB0_702:
	v_add_u32_e32 v17, 0xb0, v161
	v_lshlrev_b32_e32 v18, 2, v17
	v_ashrrev_i32_e32 v19, 31, v18
	v_lshl_add_u64 v[18:19], v[18:19], 2, s[14:15]
	v_add_f32_e32 v16, v234, v235
	v_add_f32_e32 v18, v236, v237
	v_add_f32_e32 v16, v16, v18
	v_fmamk_f32 v16, v16, 0x3c000000, v147
	v_mul_f32_e32 v18, 0x4f800000, v16
	v_cmp_gt_f32_e32 vcc, s69, v16
	v_ashrrev_i32_e32 v19, 9, v17
	s_nop 0
	v_cndmask_b32_e32 v16, v16, v18, vcc
	v_sqrt_f32_e32 v18, v16
	s_nop 0
	v_add_u32_e32 v20, -1, v18
	v_add_u32_e32 v21, 1, v18
	v_fma_f32 v22, -v20, v18, v16
	v_fma_f32 v23, -v21, v18, v16
	v_cmp_ge_f32_e64 s[10:11], 0, v22
	s_nop 1
	v_cndmask_b32_e64 v18, v18, v20, s[10:11]
	v_cmp_lt_f32_e64 s[10:11], 0, v23
	s_nop 1
	v_cndmask_b32_e64 v18, v18, v21, s[10:11]
	v_mul_f32_e32 v20, 0x37800000, v18
	v_cndmask_b32_e32 v18, v18, v20, vcc
	v_cmp_class_f32_e32 vcc, v16, v148
	s_nop 1
	v_cndmask_b32_e32 v16, v18, v16, vcc
	v_div_scale_f32 v20, s[10:11], v16, v16, 1.0
	v_rcp_f32_e32 v21, v20
	v_and_b32_e32 v18, -8, v19
	v_div_scale_f32 v19, vcc, 1.0, v16, 1.0
	v_fma_f32 v22, -v20, v21, 1.0
	v_fmac_f32_e32 v21, v22, v21
	v_mul_f32_e32 v22, v19, v21
	v_fma_f32 v23, -v20, v22, v19
	v_fmac_f32_e32 v22, v23, v21
	v_fma_f32 v19, -v20, v22, v19
	v_div_fmas_f32 v19, v19, v21, v22
	s_and_b64 vcc, exec, s[6:7]
	v_div_fixup_f32 v16, v19, v16, 1.0
	s_mov_b64 s[6:7], -1
	s_cbranch_vccz .LBB0_705
	s_andn2_b64 vcc, exec, s[6:7]
	s_cbranch_vccz .LBB0_706
